# v20 + P3 second-GEMM third-round units moved to workgroups 16-31 with flag sync + diff epilogue gain loads batched + fox cumsum rewrite + more weight conversion in P1 idle workgroups
# baseline (speedup 1.0000x reference)
; __device__ __forceinline__ unsigned cvt_pk_bf16(float lo, float hi) { unsigned r; asm volatile("v_cvt_pk_bf16_f32 %0, %1, %2" : "=v"(r) : "v"(lo), "v"(hi)); return r; }
; __device__ __forceinline__ int crow(int r, int hi) { return (r & 3) + 8 * (r >> 2) + 4 * hi; }
; template <int MODE>
; __device__ __forceinline__ void attn_unit(const AttnP& P, int b, int h, int u, int j0, char* lds, float lam) {
;     ...
;   if (hi == 0) li_l[r32] = l_reg; asm volatile("s_waitcnt lgkmcnt(0)" ::: "memory");
;   float rli[16];
; #pragma unroll
;   for (int r = 0; r < 16; ++r) rli[r] = __builtin_amdgcn_rcpf(li_l[crow(r, hi)]);
;   if (MODE == 1) {
;     bf16_t* Ow = P.att + (size_t)(rowbase + qw) * 2048 + 1024 + h * 128 + r32;
; #pragma unroll
;     for (int r = 0; r < 16; ++r) { const int orow = crow(r, hi);
; #pragma unroll
;       for (int d0 = 0; d0 < 4; ++d0) Ow[(size_t)orow * 2048 + d0 * 32] = (bf16_t)(cvt_pk_bf16(o[d0][r] * rli[r], 0.f) & 0xffffu); }
;   } else {
;     float* xo = (float*)(lds + (map ? OFF_XCH : OFF_G)) + qg * (32 * 128);
; #pragma unroll
;     for (int r = 0; r < 16; ++r) { const int orow = crow(r, hi);
; #pragma unroll
;       for (int d0 = 0; d0 < 4; ++d0) xo[orow * 128 + d0 * 32 + r32] = o[d0][r] * rli[r]; }
;     __syncthreads();
;     { const int row = tid >> 2, q4 = tid & 3;
;       const float* x1 = (const float*)(lds + OFF_G) + row * 128 + 32 * q4; const float* x2 = (const float*)(lds + OFF_XCH) + row * 128 + 32 * q4;
;       f32x4 v[8]; float ss = 0.f;
; #pragma unroll
;       for (int i = 0; i < 8; ++i) { v[i] = *(const f32x4*)(x1 + 4 * i) - lam * *(const f32x4*)(x2 + 4 * i); ss += (v[i].x * v[i].x + v[i].y * v[i].y) + (v[i].z * v[i].z + v[i].w * v[i].w); }
.LBB0_300:
	s_or_b64 exec, exec, s[12:13]
	s_waitcnt lgkmcnt(0)
	ds_read_b128 v[4:7], v192
	ds_read_b128 v[8:11], v192 offset:32
	v_mov_b32_e32 v179, v3
	s_add_i32 s29, s29, s82
	s_add_i32 s28, s28, s82
	s_waitcnt lgkmcnt(1)
	v_rcp_f32_e32 v2, v4
	v_rcp_f32_e32 v12, v5
	v_rcp_f32_e32 v13, v6
	v_rcp_f32_e32 v14, v7
	v_mul_f32_e32 v50, v50, v2
	v_mul_f32_e32 v66, v66, v2
	v_mul_f32_e32 v18, v18, v2
	v_mul_f32_e32 v2, v34, v2
	s_waitcnt lgkmcnt(0)
	v_rcp_f32_e32 v15, v8
	ds_read_b128 v[4:7], v192 offset:64
	v_rcp_f32_e32 v16, v9
	v_rcp_f32_e32 v17, v10
	v_rcp_f32_e32 v82, v11
	ds_read_b128 v[8:11], v192 offset:96
	ds_write2_b32 v223, v18, v2 offset0:64 offset1:96
	v_mul_f32_e32 v2, v51, v12
	v_mul_f32_e32 v18, v67, v12
	ds_write2_b32 v223, v2, v18 offset0:128 offset1:160
	v_mul_f32_e32 v2, v19, v12
	v_mul_f32_e32 v12, v35, v12
	ds_write2_b32 v223, v2, v12 offset0:192 offset1:224
	v_mul_f32_e32 v2, v52, v13
	v_mul_f32_e32 v12, v68, v13
	ds_write2_b32 v193, v2, v12 offset1:32
	v_mul_f32_e32 v2, v20, v13
	v_mul_f32_e32 v12, v36, v13
	ds_write2_b32 v193, v2, v12 offset0:64 offset1:96
	v_mul_f32_e32 v2, v53, v14
	v_mul_f32_e32 v12, v69, v14
	ds_write2_b32 v193, v2, v12 offset0:128 offset1:160
	v_mul_f32_e32 v2, v21, v14
	v_mul_f32_e32 v12, v37, v14
	ds_write2_b32 v193, v2, v12 offset0:192 offset1:224
	v_mul_f32_e32 v2, v54, v15
	v_mul_f32_e32 v12, v70, v15
	ds_write2_b32 v194, v2, v12 offset1:32
	v_mul_f32_e32 v2, v22, v15
	v_mul_f32_e32 v12, v38, v15
	ds_write2_b32 v194, v2, v12 offset0:64 offset1:96
	v_mul_f32_e32 v2, v55, v16
	v_mul_f32_e32 v12, v71, v16
	ds_write2_b32 v194, v2, v12 offset0:128 offset1:160
	v_mul_f32_e32 v2, v23, v16
	v_mul_f32_e32 v12, v39, v16
	s_waitcnt lgkmcnt(11)
	v_rcp_f32_e32 v4, v4
	ds_write2_b32 v194, v2, v12 offset0:192 offset1:224
	v_mul_f32_e32 v2, v56, v17
	v_mul_f32_e32 v12, v72, v17
	ds_write2_b32 v231, v2, v12 offset1:32
	v_mul_f32_e32 v2, v24, v17
	v_mul_f32_e32 v12, v40, v17
	v_rcp_f32_e32 v5, v5
	ds_write2_b32 v231, v2, v12 offset0:64 offset1:96
	v_mul_f32_e32 v2, v57, v82
	v_mul_f32_e32 v12, v73, v82
	ds_write2_b32 v231, v2, v12 offset0:128 offset1:160
	v_mul_f32_e32 v2, v25, v82
	v_mul_f32_e32 v12, v41, v82
	v_rcp_f32_e32 v6, v6
	ds_write2_b32 v231, v2, v12 offset0:192 offset1:224
	v_mul_f32_e32 v2, v58, v4
	v_mul_f32_e32 v12, v74, v4
	ds_write2_b32 v232, v2, v12 offset1:32
	v_mul_f32_e32 v2, v26, v4
	v_mul_f32_e32 v4, v42, v4
	v_rcp_f32_e32 v7, v7
	ds_write2_b32 v232, v2, v4 offset0:64 offset1:96
	v_mul_f32_e32 v2, v59, v5
	v_mul_f32_e32 v4, v75, v5
	ds_write2_b32 v232, v2, v4 offset0:128 offset1:160
	v_mul_f32_e32 v2, v27, v5
	v_mul_f32_e32 v4, v43, v5
	s_waitcnt lgkmcnt(14)
	v_rcp_f32_e32 v8, v8
	ds_write2_b32 v232, v2, v4 offset0:192 offset1:224
	v_mul_f32_e32 v2, v60, v6
	v_mul_f32_e32 v4, v76, v6
	ds_write2_b32 v233, v2, v4 offset1:32
	v_mul_f32_e32 v2, v28, v6
	v_mul_f32_e32 v4, v44, v6
	v_rcp_f32_e32 v9, v9
	ds_write2_b32 v233, v2, v4 offset0:64 offset1:96
	v_mul_f32_e32 v2, v61, v7
	v_mul_f32_e32 v4, v77, v7
	ds_write2_b32 v233, v2, v4 offset0:128 offset1:160
	v_mul_f32_e32 v2, v29, v7
	v_mul_f32_e32 v4, v45, v7
	v_rcp_f32_e32 v10, v10
	ds_write2_b32 v233, v2, v4 offset0:192 offset1:224
	v_mul_f32_e32 v2, v62, v8
	v_mul_f32_e32 v4, v78, v8
	ds_write2_b32 v234, v2, v4 offset1:32
	v_mul_f32_e32 v2, v30, v8
	v_mul_f32_e32 v4, v46, v8
	v_rcp_f32_e32 v11, v11
	ds_write2_b32 v234, v2, v4 offset0:64 offset1:96
	v_mul_f32_e32 v2, v63, v9
	v_mul_f32_e32 v4, v79, v9
	ds_write2_b32 v234, v2, v4 offset0:128 offset1:160
	v_mul_f32_e32 v2, v31, v9
	v_mul_f32_e32 v4, v47, v9
	ds_write2_b32 v234, v2, v4 offset0:192 offset1:224
	v_mul_f32_e32 v2, v64, v10
	v_mul_f32_e32 v4, v80, v10
	ds_write2_b32 v235, v2, v4 offset1:32
	v_mul_f32_e32 v2, v32, v10
	v_mul_f32_e32 v4, v48, v10
	ds_write2_b32 v235, v2, v4 offset0:64 offset1:96
	v_mul_f32_e32 v2, v65, v11
	v_mul_f32_e32 v4, v81, v11
	ds_write2_b32 v235, v2, v4 offset0:128 offset1:160
	v_mul_f32_e32 v2, v33, v11
	v_mul_f32_e32 v4, v49, v11
	ds_write2_b32 v223, v50, v66 offset1:32
	ds_write2_b32 v235, v2, v4 offset0:192 offset1:224
	s_waitcnt lgkmcnt(0)
	s_barrier
	ds_read_b128 v[4:7], v225
	ds_read_b128 v[8:11], v225 offset:16
	ds_read_b128 v[12:15], v227
	ds_read_b128 v[16:19], v225 offset:32
	ds_read_b128 v[20:23], v225 offset:48
	ds_read_b128 v[24:27], v227 offset:16
	ds_read_b128 v[28:31], v227 offset:32
	ds_read_b128 v[32:35], v227 offset:48
	s_waitcnt lgkmcnt(5)
	v_pk_fma_f32 v[38:39], v[166:167], v[12:13], v[4:5] neg_lo:[1,0,0] neg_hi:[1,0,0]
	v_pk_fma_f32 v[36:37], v[176:177], v[14:15], v[6:7]
	s_waitcnt lgkmcnt(2)
	v_pk_fma_f32 v[42:43], v[166:167], v[24:25], v[8:9] neg_lo:[1,0,0] neg_hi:[1,0,0]
	v_pk_fma_f32 v[40:41], v[176:177], v[26:27], v[10:11]
	v_mov_b32_e32 v6, v39
	v_mov_b32_e32 v7, v43
	v_mov_b32_e32 v4, v38
	v_mov_b32_e32 v5, v42
	v_pk_mul_f32 v[6:7], v[6:7], v[6:7]
	v_mov_b32_e32 v8, v37
	v_mov_b32_e32 v9, v41
	v_pk_fma_f32 v[4:5], v[4:5], v[4:5], v[6:7]
	v_mov_b32_e32 v6, v36
	v_mov_b32_e32 v7, v40
	v_pk_mul_f32 v[8:9], v[8:9], v[8:9]
	s_waitcnt lgkmcnt(1)
	v_pk_fma_f32 v[30:31], v[176:177], v[30:31], v[18:19]
	v_pk_fma_f32 v[6:7], v[6:7], v[6:7], v[8:9]
	v_pk_fma_f32 v[28:29], v[166:167], v[28:29], v[16:17] neg_lo:[1,0,0] neg_hi:[1,0,0]
	v_pk_add_f32 v[44:45], v[4:5], v[6:7]
	v_pk_mul_f32 v[4:5], v[28:29], v[28:29]
	v_pk_mul_f32 v[6:7], v[30:31], v[30:31]
	s_waitcnt lgkmcnt(0)
; __device__ __forceinline__ u32x4 pack8(const f32x4 a, const f32x4 b) { u32x4 w; w.x = cvt_pk_bf16(a[0], a[1]); w.y = cvt_pk_bf16(a[2], a[3]); w.z = cvt_pk_bf16(b[0], b[1]); w.w = cvt_pk_bf16(b[2], b[3]); return w; }
; template <int MODE>
; __device__ __forceinline__ void attn_unit(const AttnP& P, int b, int h, int u, int j0, char* lds, float lam) {
;     ...
;     { const int row = tid >> 2, q4 = tid & 3;
;       const float* x1 = (const float*)(lds + OFF_G) + row * 128 + 32 * q4; const float* x2 = (const float*)(lds + OFF_XCH) + row * 128 + 32 * q4;
;       f32x4 v[8]; float ss = 0.f;
; #pragma unroll
;       for (int i = 0; i < 8; ++i) { v[i] = *(const f32x4*)(x1 + 4 * i) - lam * *(const f32x4*)(x2 + 4 * i); ss += (v[i].x * v[i].x + v[i].y * v[i].y) + (v[i].z * v[i].z + v[i].w * v[i].w); }
;       ss += __shfl_xor(ss, 1); ss += __shfl_xor(ss, 2);
;       const float rs = rsqrtf(ss * (1.f / 128.f) + EPS) * (1.f - LAM_INIT);
;       bf16_t* Ow = P.att + (size_t)(rowbase + 128 * u + row) * 2048 + h * 128 + 32 * q4;
; #pragma unroll
;       for (int i = 0; i < 4; ++i) { const f32x4 s0 = *(const f32x4*)(P.subln + 32 * q4 + 8 * i), s1 = *(const f32x4*)(P.subln + 32 * q4 + 8 * i + 4);
;         *(u32x4*)(Ow + 8 * i) = pack8(v[2 * i] * s0 * rs, v[2 * i + 1] * s1 * rs); } }
	v_pk_fma_f32 v[34:35], v[176:177], v[34:35], v[22:23]
	v_pk_mov_b32 v[8:9], v[4:5], v[6:7] op_sel:[1,0]
	v_mov_b32_e32 v5, v7
	v_pk_add_f32 v[46:47], v[8:9], v[4:5]
	ds_read_b128 v[4:7], v225 offset:64
	ds_read_b128 v[8:11], v227 offset:64
	v_pk_fma_f32 v[32:33], v[166:167], v[32:33], v[20:21] neg_lo:[1,0,0] neg_hi:[1,0,0]
	ds_read_b128 v[12:15], v225 offset:80
	ds_read_b128 v[16:19], v227 offset:80
	global_load_dwordx4 v[20:23], v[172:173], off offset:16
	global_load_dwordx4 v[24:27], v[172:173], off
	global_load_dwordx4 v[60:63], v[172:173], off offset:32
	global_load_dwordx4 v[64:67], v[172:173], off offset:48
	global_load_dwordx4 v[68:71], v[172:173], off offset:64
	global_load_dwordx4 v[72:75], v[172:173], off offset:80
	global_load_dwordx4 v[76:79], v[172:173], off offset:96
	global_load_dwordx4 v[80:83], v[172:173], off offset:112
	s_cmpk_gt_i32 s29, 0x1ff
	s_waitcnt lgkmcnt(2)
	v_pk_fma_f32 v[50:51], v[166:167], v[8:9], v[4:5] neg_lo:[1,0,0] neg_hi:[1,0,0]
	v_pk_fma_f32 v[48:49], v[176:177], v[10:11], v[6:7]
	v_mul_f32_e32 v2, v50, v50
	v_mul_f32_e32 v8, v51, v51
	v_pk_add_f32 v[4:5], v[44:45], v[44:45] op_sel:[0,1] op_sel_hi:[1,0]
	v_pk_add_f32 v[6:7], v[46:47], v[46:47] op_sel:[0,1] op_sel_hi:[1,0]
	v_mov_b32_e32 v5, v2
	v_mov_b32_e32 v7, v8
	v_mul_f32_e32 v2, v33, v33
	v_mul_f32_e32 v9, v48, v48
	v_pk_add_f32 v[4:5], v[4:5], v[6:7]
	v_pk_fma_f32 v[6:7], v[32:33], v[32:33], v[2:3] op_sel_hi:[1,1,0]
	v_mul_f32_e32 v2, v35, v35
	v_mul_f32_e32 v10, v49, v49
	v_mov_b32_e32 v7, v9
	v_pk_fma_f32 v[8:9], v[34:35], v[34:35], v[2:3] op_sel_hi:[1,1,0]
	s_waitcnt lgkmcnt(0)
	v_pk_fma_f32 v[46:47], v[176:177], v[18:19], v[14:15]
	v_mov_b32_e32 v9, v10
	v_pk_add_f32 v[6:7], v[6:7], v[8:9]
	v_pk_fma_f32 v[52:53], v[166:167], v[16:17], v[12:13] neg_lo:[1,0,0] neg_hi:[1,0,0]
	v_pk_add_f32 v[44:45], v[4:5], v[6:7]
	ds_read_b128 v[4:7], v227 offset:96
	ds_read_b128 v[8:11], v225 offset:96
	ds_read_b128 v[12:15], v225 offset:112
	ds_read_b128 v[16:19], v227 offset:112
	v_pk_mul_f32 v[54:55], v[52:53], v[52:53]
	v_pk_mul_f32 v[56:57], v[46:47], v[46:47]
	s_waitcnt lgkmcnt(0)
	v_pk_fma_f32 v[12:13], v[166:167], v[16:17], v[12:13] neg_lo:[1,0,0] neg_hi:[1,0,0]
	v_pk_mov_b32 v[58:59], v[54:55], v[56:57] op_sel:[1,0]
	v_mov_b32_e32 v55, v57
	v_pk_add_f32 v[54:55], v[58:59], v[54:55]
	v_pk_fma_f32 v[56:57], v[176:177], v[6:7], v[10:11]
	v_pk_fma_f32 v[58:59], v[166:167], v[4:5], v[8:9] neg_lo:[1,0,0] neg_hi:[1,0,0]
	v_mul_f32_e32 v2, v12, v12
	v_mul_f32_e32 v8, v13, v13
	v_pk_add_f32 v[4:5], v[44:45], v[44:45] op_sel:[0,1] op_sel_hi:[1,0]
	v_pk_add_f32 v[6:7], v[54:55], v[54:55] op_sel:[0,1] op_sel_hi:[1,0]
	v_pk_fma_f32 v[14:15], v[176:177], v[18:19], v[14:15]
	v_mov_b32_e32 v5, v2
	v_mov_b32_e32 v7, v8
	v_mul_f32_e32 v2, v59, v59
	v_mul_f32_e32 v9, v14, v14
	v_pk_add_f32 v[4:5], v[4:5], v[6:7]
	v_pk_fma_f32 v[6:7], v[58:59], v[58:59], v[2:3] op_sel_hi:[1,1,0]
	v_mul_f32_e32 v2, v57, v57
	v_mul_f32_e32 v10, v15, v15
	v_mov_b32_e32 v7, v9
	v_pk_fma_f32 v[8:9], v[56:57], v[56:57], v[2:3] op_sel_hi:[1,1,0]
	s_nop 0
	v_mov_b32_e32 v9, v10
	v_pk_add_f32 v[6:7], v[6:7], v[8:9]
	s_waitcnt vmcnt(0)
	v_pk_mul_f32 v[8:9], v[42:43], v[20:21]
	v_pk_add_f32 v[4:5], v[4:5], v[6:7]
	s_waitcnt vmcnt(0)
	v_pk_mul_f32 v[6:7], v[36:37], v[26:27]
	v_add_f32_e32 v2, v4, v5
	ds_bpermute_b32 v4, v165, v2
	v_pk_mul_f32 v[10:11], v[40:41], v[22:23]
	s_waitcnt lgkmcnt(0)
	v_add_f32_e32 v2, v2, v4
	ds_bpermute_b32 v4, v196, v2
	s_waitcnt lgkmcnt(0)
	v_add_f32_e32 v2, v2, v4
	v_fmamk_f32 v2, v2, 0x3c000000, v229
	v_mul_f32_e32 v4, 0x4b800000, v2
	v_cmp_gt_f32_e32 vcc, s27, v2
	s_nop 1
	v_cndmask_b32_e32 v2, v2, v4, vcc
	v_rsq_f32_e32 v2, v2
	s_nop 0
	v_mul_f32_e32 v4, 0x45800000, v2
	v_cndmask_b32_e32 v2, v2, v4, vcc
	v_mul_f32_e32 v16, 0x3f4ccccd, v2
	v_add_lshl_u32 v2, v236, s16, 12
	v_lshl_add_u64 v[4:5], s[46:47], 0, v[2:3]
	v_lshl_add_u64 v[4:5], v[4:5], 0, s[0:1]
	v_lshl_add_u64 v[18:19], v[4:5], 0, v[178:179]
	v_pk_mul_f32 v[4:5], v[38:39], v[24:25]
	v_pk_mul_f32 v[6:7], v[6:7], v[16:17] op_sel_hi:[1,0]
	v_pk_mul_f32 v[4:5], v[4:5], v[16:17] op_sel_hi:[1,0]
	v_pk_mul_f32 v[10:11], v[10:11], v[16:17] op_sel_hi:[1,0]
	v_pk_mul_f32 v[8:9], v[8:9], v[16:17] op_sel_hi:[1,0]
	v_cvt_pk_bf16_f32 v4, v4, v5
	v_cvt_pk_bf16_f32 v5, v6, v7
	s_nop 0
	v_cvt_pk_bf16_f32 v6, v8, v9
	v_cvt_pk_bf16_f32 v7, v10, v11
	global_store_dwordx4 v[18:19], v[4:7], off
	v_pk_mul_f32 v[60:61], v[28:29], v[60:61]
	v_pk_mul_f32 v[62:63], v[30:31], v[62:63]
	v_pk_mul_f32 v[64:65], v[32:33], v[64:65]
	v_pk_mul_f32 v[66:67], v[34:35], v[66:67]
	v_pk_mul_f32 v[60:61], v[60:61], v[16:17] op_sel_hi:[1,0]
	v_pk_mul_f32 v[62:63], v[62:63], v[16:17] op_sel_hi:[1,0]
	v_pk_mul_f32 v[64:65], v[64:65], v[16:17] op_sel_hi:[1,0]
	v_pk_mul_f32 v[66:67], v[66:67], v[16:17] op_sel_hi:[1,0]
	v_cvt_pk_bf16_f32 v60, v60, v61
	v_cvt_pk_bf16_f32 v61, v62, v63
	v_cvt_pk_bf16_f32 v62, v64, v65
	v_cvt_pk_bf16_f32 v63, v66, v67
	global_store_dwordx4 v[18:19], v[60:63], off offset:16
	v_pk_mul_f32 v[68:69], v[50:51], v[68:69]
	v_pk_mul_f32 v[70:71], v[48:49], v[70:71]
	v_pk_mul_f32 v[72:73], v[52:53], v[72:73]
	v_pk_mul_f32 v[74:75], v[46:47], v[74:75]
	v_pk_mul_f32 v[68:69], v[68:69], v[16:17] op_sel_hi:[1,0]
	v_pk_mul_f32 v[70:71], v[70:71], v[16:17] op_sel_hi:[1,0]
	v_pk_mul_f32 v[72:73], v[72:73], v[16:17] op_sel_hi:[1,0]
	v_pk_mul_f32 v[74:75], v[74:75], v[16:17] op_sel_hi:[1,0]
	v_cvt_pk_bf16_f32 v68, v68, v69
	v_cvt_pk_bf16_f32 v69, v70, v71
	v_cvt_pk_bf16_f32 v70, v72, v73
	v_cvt_pk_bf16_f32 v71, v74, v75
	global_store_dwordx4 v[18:19], v[68:71], off offset:32
	v_pk_mul_f32 v[76:77], v[58:59], v[76:77]
	v_pk_mul_f32 v[78:79], v[56:57], v[78:79]
	v_pk_mul_f32 v[80:81], v[12:13], v[80:81]
	v_pk_mul_f32 v[82:83], v[14:15], v[82:83]
	v_pk_mul_f32 v[76:77], v[76:77], v[16:17] op_sel_hi:[1,0]
	v_pk_mul_f32 v[78:79], v[78:79], v[16:17] op_sel_hi:[1,0]
	v_pk_mul_f32 v[80:81], v[80:81], v[16:17] op_sel_hi:[1,0]
	v_pk_mul_f32 v[82:83], v[82:83], v[16:17] op_sel_hi:[1,0]
	v_cvt_pk_bf16_f32 v76, v76, v77
	v_cvt_pk_bf16_f32 v77, v78, v79
	v_cvt_pk_bf16_f32 v78, v80, v81
	v_cvt_pk_bf16_f32 v79, v82, v83
	global_store_dwordx4 v[18:19], v[76:79], off offset:48
	s_barrier
	s_cbranch_scc1 .LBB0_341

; __device__ __forceinline__ unsigned cvt_pk_bf16(float lo, float hi) { unsigned r; asm volatile("v_cvt_pk_bf16_f32 %0, %1, %2" : "=v"(r) : "v"(lo), "v"(hi)); return r; }
; __device__ __forceinline__ int crow(int r, int hi) { return (r & 3) + 8 * (r >> 2) + 4 * hi; }
; template <int MODE>
; __device__ __forceinline__ void attn_unit(const AttnP& P, int b, int h, int u, int j0, char* lds, float lam) {
;     ...
;   if (hi == 0) li_l[r32] = l_reg; asm volatile("s_waitcnt lgkmcnt(0)" ::: "memory");
;   float rli[16];
; #pragma unroll
;   for (int r = 0; r < 16; ++r) rli[r] = __builtin_amdgcn_rcpf(li_l[crow(r, hi)]);
;   if (MODE == 1) {
;     bf16_t* Ow = P.att + (size_t)(rowbase + qw) * 2048 + 1024 + h * 128 + r32;
; #pragma unroll
;     for (int r = 0; r < 16; ++r) { const int orow = crow(r, hi);
; #pragma unroll
;       for (int d0 = 0; d0 < 4; ++d0) Ow[(size_t)orow * 2048 + d0 * 32] = (bf16_t)(cvt_pk_bf16(o[d0][r] * rli[r], 0.f) & 0xffffu); }
;   } else {
;     float* xo = (float*)(lds + (map ? OFF_XCH : OFF_G)) + qg * (32 * 128);
; #pragma unroll
;     for (int r = 0; r < 16; ++r) { const int orow = crow(r, hi);
; #pragma unroll
;       for (int d0 = 0; d0 < 4; ++d0) xo[orow * 128 + d0 * 32 + r32] = o[d0][r] * rli[r]; }
;     __syncthreads();
.LBB0_320:
	s_and_saveexec_b64 s[14:15], s[2:3]
	ds_write_b32 v218, v232
	s_or_b64 exec, exec, s[14:15]
	s_waitcnt lgkmcnt(0)
	v_add_u32_e32 v192, v210, v215
	ds_read_b128 v[68:71], v192
	ds_read_b128 v[72:75], v192 offset:32
	v_add_u32_e32 v193, 0x400, v223
	v_add_u32_e32 v194, 0x1000, v223
	v_add_u32_e32 v231, 0x1400, v223
	s_waitcnt lgkmcnt(1)
	v_rcp_f32_e32 v76, v68
	v_rcp_f32_e32 v77, v69
	v_rcp_f32_e32 v78, v70
	v_rcp_f32_e32 v79, v71
	v_mul_f32_e32 v4, v4, v76
	v_mul_f32_e32 v52, v52, v76
	s_waitcnt lgkmcnt(0)
	v_rcp_f32_e32 v80, v72
	ds_read_b128 v[68:71], v192 offset:64
	v_rcp_f32_e32 v81, v73
	v_rcp_f32_e32 v82, v74
	v_rcp_f32_e32 v83, v75
	ds_read_b128 v[72:75], v192 offset:96
	ds_write2_b32 v223, v4, v52 offset1:32
	v_mul_f32_e32 v4, v20, v76
	v_mul_f32_e32 v20, v36, v76
	ds_write2_b32 v223, v4, v20 offset0:64 offset1:96
	v_mul_f32_e32 v4, v5, v77
	v_mul_f32_e32 v5, v53, v77
	ds_write2_b32 v223, v4, v5 offset0:128 offset1:160
	v_mul_f32_e32 v4, v21, v77
	v_mul_f32_e32 v5, v37, v77
	ds_write2_b32 v223, v4, v5 offset0:192 offset1:224
	v_mul_f32_e32 v4, v6, v78
	v_mul_f32_e32 v5, v54, v78
	ds_write2_b32 v193, v4, v5 offset1:32
	v_mul_f32_e32 v4, v22, v78
	v_mul_f32_e32 v5, v38, v78
	ds_write2_b32 v193, v4, v5 offset0:64 offset1:96
	v_mul_f32_e32 v4, v7, v79
	v_mul_f32_e32 v5, v55, v79
	ds_write2_b32 v193, v4, v5 offset0:128 offset1:160
	v_mul_f32_e32 v4, v23, v79
	v_mul_f32_e32 v5, v39, v79
	ds_write2_b32 v193, v4, v5 offset0:192 offset1:224
	v_mul_f32_e32 v4, v8, v80
	v_mul_f32_e32 v5, v56, v80
	ds_write2_b32 v194, v4, v5 offset1:32
	v_mul_f32_e32 v4, v24, v80
	v_mul_f32_e32 v5, v40, v80
	ds_write2_b32 v194, v4, v5 offset0:64 offset1:96
	v_mul_f32_e32 v4, v9, v81
	v_mul_f32_e32 v5, v57, v81
	ds_write2_b32 v194, v4, v5 offset0:128 offset1:160
	v_mul_f32_e32 v4, v25, v81
	v_mul_f32_e32 v5, v41, v81
	s_waitcnt lgkmcnt(12)
	v_rcp_f32_e32 v68, v68
	ds_write2_b32 v194, v4, v5 offset0:192 offset1:224
	v_mul_f32_e32 v4, v10, v82
	v_mul_f32_e32 v5, v58, v82
	ds_write2_b32 v231, v4, v5 offset1:32
	v_mul_f32_e32 v4, v26, v82
	v_mul_f32_e32 v5, v42, v82
	v_rcp_f32_e32 v69, v69
	ds_write2_b32 v231, v4, v5 offset0:64 offset1:96
	v_mul_f32_e32 v4, v11, v83
	v_mul_f32_e32 v5, v59, v83
	ds_write2_b32 v231, v4, v5 offset0:128 offset1:160
	v_mul_f32_e32 v4, v27, v83
	v_mul_f32_e32 v5, v43, v83
	v_rcp_f32_e32 v70, v70
	ds_write2_b32 v231, v4, v5 offset0:192 offset1:224
	v_mul_f32_e32 v4, v12, v68
	v_mul_f32_e32 v5, v60, v68
	v_add_u32_e32 v232, 0x2000, v223
	ds_write2_b32 v232, v4, v5 offset1:32
	v_mul_f32_e32 v4, v28, v68
	v_mul_f32_e32 v5, v44, v68
	v_rcp_f32_e32 v71, v71
	ds_write2_b32 v232, v4, v5 offset0:64 offset1:96
	v_mul_f32_e32 v4, v13, v69
	v_mul_f32_e32 v5, v61, v69
	ds_write2_b32 v232, v4, v5 offset0:128 offset1:160
	v_mul_f32_e32 v4, v29, v69
	v_mul_f32_e32 v5, v45, v69
	s_waitcnt lgkmcnt(14)
	v_rcp_f32_e32 v72, v72
	ds_write2_b32 v232, v4, v5 offset0:192 offset1:224
	v_mul_f32_e32 v4, v14, v70
	v_mul_f32_e32 v5, v62, v70
	v_add_u32_e32 v233, 0x2400, v223
	ds_write2_b32 v233, v4, v5 offset1:32
	v_mul_f32_e32 v4, v30, v70
	v_mul_f32_e32 v5, v46, v70
	v_rcp_f32_e32 v73, v73
	ds_write2_b32 v233, v4, v5 offset0:64 offset1:96
	v_mul_f32_e32 v4, v15, v71
	v_mul_f32_e32 v5, v63, v71
	ds_write2_b32 v233, v4, v5 offset0:128 offset1:160
	v_mul_f32_e32 v4, v31, v71
	v_mul_f32_e32 v5, v47, v71
	v_rcp_f32_e32 v74, v74
	ds_write2_b32 v233, v4, v5 offset0:192 offset1:224
	v_mul_f32_e32 v4, v16, v72
	v_mul_f32_e32 v5, v64, v72
	v_add_u32_e32 v234, 0x3000, v223
	ds_write2_b32 v234, v4, v5 offset1:32
	v_mul_f32_e32 v4, v32, v72
	v_mul_f32_e32 v5, v48, v72
	v_rcp_f32_e32 v75, v75
	ds_write2_b32 v234, v4, v5 offset0:64 offset1:96
	v_mul_f32_e32 v4, v17, v73
	v_mul_f32_e32 v5, v65, v73
	ds_write2_b32 v234, v4, v5 offset0:128 offset1:160
	v_mul_f32_e32 v4, v33, v73
	v_mul_f32_e32 v5, v49, v73
	ds_write2_b32 v234, v4, v5 offset0:192 offset1:224
	v_mul_f32_e32 v4, v18, v74
	v_mul_f32_e32 v5, v66, v74
	v_add_u32_e32 v235, 0x3400, v223
	ds_write2_b32 v235, v4, v5 offset1:32
	v_mul_f32_e32 v4, v34, v74
	v_mul_f32_e32 v5, v50, v74
	ds_write2_b32 v235, v4, v5 offset0:64 offset1:96
	v_mul_f32_e32 v4, v19, v75
	v_mul_f32_e32 v5, v67, v75
	ds_write2_b32 v235, v4, v5 offset0:128 offset1:160
	v_mul_f32_e32 v4, v35, v75
	v_mul_f32_e32 v5, v51, v75
	ds_write2_b32 v235, v4, v5 offset0:192 offset1:224
	s_waitcnt lgkmcnt(0)
	s_barrier
; template <int MODE>
; __device__ __forceinline__ void attn_unit(const AttnP& P, int b, int h, int u, int j0, char* lds, float lam) {
;     ...
;     { const int row = tid >> 2, q4 = tid & 3;
;       const float* x1 = (const float*)(lds + OFF_G) + row * 128 + 32 * q4; const float* x2 = (const float*)(lds + OFF_XCH) + row * 128 + 32 * q4;
;       f32x4 v[8]; float ss = 0.f;
; #pragma unroll
;       for (int i = 0; i < 8; ++i) { v[i] = *(const f32x4*)(x1 + 4 * i) - lam * *(const f32x4*)(x2 + 4 * i); ss += (v[i].x * v[i].x + v[i].y * v[i].y) + (v[i].z * v[i].z + v[i].w * v[i].w); }
;       ss += __shfl_xor(ss, 1); ss += __shfl_xor(ss, 2);
;       const float rs = rsqrtf(ss * (1.f / 128.f) + EPS) * (1.f - LAM_INIT);
	ds_read_b128 v[4:7], v225
	ds_read_b128 v[8:11], v225 offset:16
	ds_read_b128 v[12:15], v225 offset:32
	ds_read_b128 v[16:19], v225 offset:48
	ds_read_b128 v[20:23], v227
	ds_read_b128 v[24:27], v227 offset:16
	ds_read_b128 v[28:31], v227 offset:32
	ds_read_b128 v[32:35], v227 offset:48
	v_xor_b32_e32 v177, 0x80000000, v131
	s_waitcnt lgkmcnt(3)
	v_pk_fma_f32 v[38:39], v[166:167], v[20:21], v[4:5] neg_lo:[1,0,0] neg_hi:[1,0,0]
	s_waitcnt lgkmcnt(2)
	v_pk_fma_f32 v[42:43], v[166:167], v[24:25], v[8:9] neg_lo:[1,0,0] neg_hi:[1,0,0]
	v_pk_fma_f32 v[36:37], v[176:177], v[22:23], v[6:7]
	v_pk_fma_f32 v[40:41], v[176:177], v[26:27], v[10:11]
	v_mov_b32_e32 v6, v39
	v_mov_b32_e32 v7, v43
	v_mov_b32_e32 v4, v38
	v_mov_b32_e32 v5, v42
	v_pk_mul_f32 v[6:7], v[6:7], v[6:7]
	v_mov_b32_e32 v8, v37
	v_mov_b32_e32 v9, v41
	v_pk_fma_f32 v[4:5], v[4:5], v[4:5], v[6:7]
	v_mov_b32_e32 v6, v36
	v_mov_b32_e32 v7, v40
	v_pk_mul_f32 v[8:9], v[8:9], v[8:9]
	s_waitcnt lgkmcnt(1)
	v_pk_fma_f32 v[30:31], v[176:177], v[30:31], v[14:15]
	v_pk_fma_f32 v[6:7], v[6:7], v[6:7], v[8:9]
	v_pk_fma_f32 v[28:29], v[166:167], v[28:29], v[12:13] neg_lo:[1,0,0] neg_hi:[1,0,0]
	v_pk_add_f32 v[20:21], v[4:5], v[6:7]
	v_pk_mul_f32 v[4:5], v[28:29], v[28:29]
	v_pk_mul_f32 v[6:7], v[30:31], v[30:31]
	s_waitcnt lgkmcnt(0)
	v_pk_fma_f32 v[34:35], v[176:177], v[34:35], v[18:19]
	v_pk_mov_b32 v[8:9], v[4:5], v[6:7] op_sel:[1,0]
	v_mov_b32_e32 v5, v7
	v_pk_add_f32 v[22:23], v[8:9], v[4:5]
	ds_read_b128 v[4:7], v225 offset:64
	ds_read_b128 v[8:11], v227 offset:64
	v_pk_fma_f32 v[32:33], v[166:167], v[32:33], v[16:17] neg_lo:[1,0,0] neg_hi:[1,0,0]
	ds_read_b128 v[12:15], v225 offset:80
	ds_read_b128 v[16:19], v227 offset:80
	v_pk_add_f32 v[20:21], v[20:21], v[20:21] op_sel:[0,1] op_sel_hi:[1,0]
	v_pk_add_f32 v[22:23], v[22:23], v[22:23] op_sel:[0,1] op_sel_hi:[1,0]
	s_waitcnt lgkmcnt(2)
	v_pk_fma_f32 v[44:45], v[176:177], v[10:11], v[6:7]
	v_pk_fma_f32 v[46:47], v[166:167], v[8:9], v[4:5] neg_lo:[1,0,0] neg_hi:[1,0,0]
	global_load_dwordx4 v[4:7], v[172:173], off offset:16
	global_load_dwordx4 v[8:11], v[172:173], off
	global_load_dwordx4 v[60:63], v[172:173], off offset:32
	global_load_dwordx4 v[64:67], v[172:173], off offset:48
	global_load_dwordx4 v[68:71], v[172:173], off offset:64
	global_load_dwordx4 v[72:75], v[172:173], off offset:80
	global_load_dwordx4 v[76:79], v[172:173], off offset:96
	global_load_dwordx4 v[80:83], v[172:173], off offset:112
	v_mul_f32_e32 v24, v46, v46
	v_mul_f32_e32 v25, v47, v47
	v_mov_b32_e32 v21, v24
	v_mov_b32_e32 v23, v25
	v_pk_add_f32 v[20:21], v[20:21], v[22:23]
	v_mul_f32_e32 v22, v33, v33
	v_mul_f32_e32 v24, v35, v35
	v_mul_f32_e32 v26, v44, v44
	v_mul_f32_e32 v27, v45, v45
	v_pk_fma_f32 v[22:23], v[32:33], v[32:33], v[22:23] op_sel_hi:[1,1,0]
	v_pk_fma_f32 v[24:25], v[34:35], v[34:35], v[24:25] op_sel_hi:[1,1,0]
	v_mov_b32_e32 v23, v26
	v_mov_b32_e32 v25, v27
	v_pk_add_f32 v[22:23], v[22:23], v[24:25]
	s_waitcnt lgkmcnt(0)
	v_pk_fma_f32 v[50:51], v[176:177], v[18:19], v[14:15]
	v_pk_add_f32 v[48:49], v[20:21], v[22:23]
	v_pk_fma_f32 v[52:53], v[166:167], v[16:17], v[12:13] neg_lo:[1,0,0] neg_hi:[1,0,0]
	ds_read_b128 v[12:15], v227 offset:96
	ds_read_b128 v[16:19], v225 offset:96
	ds_read_b128 v[20:23], v225 offset:112
	ds_read_b128 v[24:27], v227 offset:112
	v_pk_mul_f32 v[54:55], v[52:53], v[52:53]
	v_pk_mul_f32 v[56:57], v[50:51], v[50:51]
	s_waitcnt lgkmcnt(2)
	v_pk_fma_f32 v[14:15], v[176:177], v[14:15], v[18:19]
	v_pk_mov_b32 v[58:59], v[54:55], v[56:57] op_sel:[1,0]
	v_mov_b32_e32 v55, v57
	s_waitcnt lgkmcnt(0)
	v_pk_fma_f32 v[18:19], v[166:167], v[24:25], v[20:21] neg_lo:[1,0,0] neg_hi:[1,0,0]
	v_pk_add_f32 v[54:55], v[58:59], v[54:55]
	v_pk_fma_f32 v[12:13], v[166:167], v[12:13], v[16:17] neg_lo:[1,0,0] neg_hi:[1,0,0]
	v_pk_fma_f32 v[16:17], v[176:177], v[26:27], v[22:23]
	v_mul_f32_e32 v22, v18, v18
	v_pk_add_f32 v[20:21], v[48:49], v[48:49] op_sel:[0,1] op_sel_hi:[1,0]
	v_mul_f32_e32 v24, v19, v19
	v_mov_b32_e32 v21, v22
	v_pk_add_f32 v[22:23], v[54:55], v[54:55] op_sel:[0,1] op_sel_hi:[1,0]
	v_mul_f32_e32 v25, v16, v16
	v_mov_b32_e32 v23, v24
	v_pk_add_f32 v[20:21], v[20:21], v[22:23]
	v_mul_f32_e32 v22, v13, v13
	v_pk_fma_f32 v[22:23], v[12:13], v[12:13], v[22:23] op_sel_hi:[1,1,0]
	v_mul_f32_e32 v24, v15, v15
	v_mul_f32_e32 v26, v17, v17
	v_mov_b32_e32 v23, v25
	v_pk_fma_f32 v[24:25], v[14:15], v[14:15], v[24:25] op_sel_hi:[1,1,0]
	v_or_b32_e32 v236, s30, v224
	v_mov_b32_e32 v25, v26
	v_pk_add_f32 v[22:23], v[22:23], v[24:25]
	s_lshl_b32 s0, s35, 1
	v_pk_add_f32 v[20:21], v[20:21], v[22:23]
	v_add_lshl_u32 v22, v236, s34, 12
	v_add_f32_e32 v20, v20, v21
	ds_bpermute_b32 v21, v165, v20
	v_mov_b32_e32 v23, v3
	v_lshl_add_u64 v[22:23], s[46:47], 0, v[22:23]
	v_lshl_add_u64 v[22:23], v[22:23], 0, s[0:1]
	v_mov_b32_e32 v179, v3
	s_waitcnt lgkmcnt(0)
	v_add_f32_e32 v20, v20, v21
	ds_bpermute_b32 v21, v196, v20
	v_lshl_add_u64 v[22:23], v[22:23], 0, v[178:179]
	v_readlane_b32 s14, v251, 56
	v_readlane_b32 s15, v251, 57
	v_mov_b32_e32 v155, v3
	s_waitcnt lgkmcnt(0)
	v_add_f32_e32 v20, v20, v21
	v_fmamk_f32 v20, v20, 0x3c000000, v229
	v_mul_f32_e32 v21, 0x4b800000, v20
	v_cmp_gt_f32_e32 vcc, s27, v20
	s_mov_b32 s17, 1
	v_mov_b32_e32 v179, 0
	v_cndmask_b32_e32 v20, v20, v21, vcc
	v_rsq_f32_e32 v20, v20
	s_waitcnt vmcnt(0)
	v_pk_mul_f32 v[4:5], v[42:43], v[4:5]
	v_mul_f32_e32 v21, 0x45800000, v20
	v_cndmask_b32_e32 v20, v20, v21, vcc
	v_mul_f32_e32 v20, 0x3f4ccccd, v20
	v_pk_mul_f32 v[6:7], v[40:41], v[6:7]
	s_waitcnt vmcnt(0)
; __device__ __forceinline__ u32x4 pack8(const f32x4 a, const f32x4 b) { u32x4 w; w.x = cvt_pk_bf16(a[0], a[1]); w.y = cvt_pk_bf16(a[2], a[3]); w.z = cvt_pk_bf16(b[0], b[1]); w.w = cvt_pk_bf16(b[2], b[3]); return w; }
; __device__ __forceinline__ int v_st(int k, int c) { const int kk = (k & ~0xC) | ((k & 4) << 1) | ((k & 8) >> 1); return ((kk >> 3) * 4 + (c >> 5)) * 512 + ((kk & 7) * 32 + (c & 31)) * 2; }
; __device__ __forceinline__ int v_rd_base(int lane) { return ((lane & 3) << 3) | (((lane >> 2) & 3) << 6) | (((lane >> 4) & 1) << 5) | (((lane >> 5) & 1) << 8); }
; #define SLOAD(k0) do { vs0 = *(const bf16x8*)(Vh + (long)((k0) + sr) * 1024 + sc); vs1 = *(const bf16x8*)(Vh + (long)((k0) + 32 + sr) * 1024 + sc); \
;     ks0 = *(const bf16x8*)(Kh + (long)((k0) + sr) * 1024 + sc); ks1 = *(const bf16x8*)(Kh + (long)((k0) + 32 + sr) * 1024 + sc); } while (0)
; #define SWRITE(bb) do { *(bf16x8*)(V_lds + (bb) * SHM_V + vst0) = vs0; *(bf16x8*)(V_lds + (bb) * SHM_V + vst1) = vs1; const int kc = sc * 2; \
;     *(bf16x8*)(K_lds + (bb) * SHM_K + KSWZ(sr, kc)) = ks0; *(bf16x8*)(K_lds + (bb) * SHM_K + KSWZ(32 + sr, kc)) = ks1; } while (0)
; template <int MODE>
; __device__ __forceinline__ void attn_unit(const AttnP& P, int b, int h, int u, int j0, char* lds, float lam) {
;     ...
;   { const bf16_t* Qw = Qb + (rowbase + qw + r32) * 1024 + h * 128 + (MODE == 0 ? map * 64 : 0) + hi * 8;
; #pragma unroll
;     for (int d0 = 0; d0 < NQ; ++d0) qr[d0] = *(const bf16x8*)(Qw + d0 * 16); }
;   const int sr = tid >> 4, sc = (tid & 15) * 8, vst0 = v_st(sr, sc), vst1 = v_st(32 + sr, sc);
;   const int vb0 = (int)(uintptr_t)V_lds + v_rd_base(lane);
;   bf16x8 vs0, vs1, ks0, ks1;
;     ...
;   float mref = 0.f, l_reg = 0.f; f32x16 o[4], negm;
; #pragma unroll
;   for (int d = 0; d < 4; ++d) o[d] = f32x16{};
;   float b15 = 0.f; if (MODE == 0) b15 = P.rel_table[15 * 8 + h] * LOG2E;
; #pragma unroll
;   for (int r = 0; r < 16; ++r) negm[r] = b15;
;   SLOAD(j0 * 64); SWRITE(j0 & 1); if (j0 + 1 < NT) SLOAD((j0 + 1) * 64);
;   __syncthreads();
;     ...
;       bf16_t* Ow = P.att + (size_t)(rowbase + 128 * u + row) * 2048 + h * 128 + 32 * q4;
; #pragma unroll
;       for (int i = 0; i < 4; ++i) { const f32x4 s0 = *(const f32x4*)(P.subln + 32 * q4 + 8 * i), s1 = *(const f32x4*)(P.subln + 32 * q4 + 8 * i + 4);
;         *(u32x4*)(Ow + 8 * i) = pack8(v[2 * i] * s0 * rs, v[2 * i + 1] * s1 * rs); } }
	v_pk_mul_f32 v[8:9], v[38:39], v[8:9]
	v_pk_mul_f32 v[10:11], v[36:37], v[10:11]
	v_pk_mul_f32 v[24:25], v[6:7], v[20:21] op_sel_hi:[1,0]
	v_pk_mul_f32 v[6:7], v[4:5], v[20:21] op_sel_hi:[1,0]
	v_pk_mul_f32 v[10:11], v[10:11], v[20:21] op_sel_hi:[1,0]
	v_pk_mul_f32 v[8:9], v[8:9], v[20:21] op_sel_hi:[1,0]
	s_nop 0
	v_cvt_pk_bf16_f32 v4, v8, v9
	v_cvt_pk_bf16_f32 v5, v10, v11
	v_cvt_pk_bf16_f32 v6, v6, v7
	v_cvt_pk_bf16_f32 v7, v24, v25
	global_store_dwordx4 v[22:23], v[4:7], off
	v_pk_mul_f32 v[60:61], v[28:29], v[60:61]
	v_pk_mul_f32 v[62:63], v[30:31], v[62:63]
	v_pk_mul_f32 v[64:65], v[32:33], v[64:65]
	v_pk_mul_f32 v[66:67], v[34:35], v[66:67]
	v_pk_mul_f32 v[60:61], v[60:61], v[20:21] op_sel_hi:[1,0]
	v_pk_mul_f32 v[62:63], v[62:63], v[20:21] op_sel_hi:[1,0]
	v_pk_mul_f32 v[64:65], v[64:65], v[20:21] op_sel_hi:[1,0]
	v_pk_mul_f32 v[66:67], v[66:67], v[20:21] op_sel_hi:[1,0]
	v_cvt_pk_bf16_f32 v60, v60, v61
	v_cvt_pk_bf16_f32 v61, v62, v63
	v_cvt_pk_bf16_f32 v62, v64, v65
	v_cvt_pk_bf16_f32 v63, v66, v67
	global_store_dwordx4 v[22:23], v[60:63], off offset:16
	v_pk_mul_f32 v[68:69], v[46:47], v[68:69]
	v_pk_mul_f32 v[70:71], v[44:45], v[70:71]
	v_pk_mul_f32 v[72:73], v[52:53], v[72:73]
	v_pk_mul_f32 v[74:75], v[50:51], v[74:75]
	v_pk_mul_f32 v[68:69], v[68:69], v[20:21] op_sel_hi:[1,0]
	v_pk_mul_f32 v[70:71], v[70:71], v[20:21] op_sel_hi:[1,0]
	v_pk_mul_f32 v[72:73], v[72:73], v[20:21] op_sel_hi:[1,0]
	v_pk_mul_f32 v[74:75], v[74:75], v[20:21] op_sel_hi:[1,0]
	v_cvt_pk_bf16_f32 v68, v68, v69
	v_cvt_pk_bf16_f32 v69, v70, v71
	v_cvt_pk_bf16_f32 v70, v72, v73
	v_cvt_pk_bf16_f32 v71, v74, v75
	global_store_dwordx4 v[22:23], v[68:71], off offset:32
	v_pk_mul_f32 v[76:77], v[12:13], v[76:77]
	v_pk_mul_f32 v[78:79], v[14:15], v[78:79]
	v_pk_mul_f32 v[80:81], v[18:19], v[80:81]
	v_pk_mul_f32 v[82:83], v[16:17], v[82:83]
	v_pk_mul_f32 v[76:77], v[76:77], v[20:21] op_sel_hi:[1,0]
	v_pk_mul_f32 v[78:79], v[78:79], v[20:21] op_sel_hi:[1,0]
	v_pk_mul_f32 v[80:81], v[80:81], v[20:21] op_sel_hi:[1,0]
	v_pk_mul_f32 v[82:83], v[82:83], v[20:21] op_sel_hi:[1,0]
	v_cvt_pk_bf16_f32 v76, v76, v77
	v_cvt_pk_bf16_f32 v77, v78, v79
	v_cvt_pk_bf16_f32 v78, v80, v81
	v_cvt_pk_bf16_f32 v79, v82, v83
	global_store_dwordx4 v[22:23], v[76:79], off offset:48
	s_barrier
	global_load_dword v82, v3, s[12:13] offset:480
	global_load_dwordx4 v[84:87], v[128:129], off
	global_load_dwordx4 v[88:91], v[190:191], off
	global_load_dwordx4 v[92:95], v[152:153], off
	global_load_dwordx4 v[96:99], v[162:163], off
	s_xor_b32 s12, s31, 63
	s_lshl_b32 s16, s12, 7
	v_add_u32_e32 v18, s16, v208
	v_add_u32_e32 v4, s30, v18
	v_or_b32_e32 v4, v4, v168
	v_mov_b32_e32 v5, v3
	v_lshlrev_b32_e32 v4, 11, v4
	v_lshl_add_u64 v[4:5], s[14:15], 0, v[4:5]
	v_lshl_add_u64 v[4:5], v[4:5], 0, s[0:1]
	v_lshl_add_u64 v[4:5], v[4:5], 0, v[2:3]
	v_lshl_add_u64 v[4:5], v[4:5], 0, v[154:155]
	global_load_dwordx4 v[132:135], v[4:5], off
	global_load_dwordx4 v[136:139], v[4:5], off offset:32
	global_load_dwordx4 v[140:143], v[4:5], off offset:64
	global_load_dwordx4 v[144:147], v[4:5], off offset:96
	s_nop 0
	global_load_dwordx4 v[160:163], v[160:161], off
	s_nop 0
	global_load_dwordx4 v[152:155], v[156:157], off
	s_nop 0
	global_load_dwordx4 v[156:159], v[158:159], off
	s_nop 0
	global_load_dwordx4 v[148:151], v[188:189], off
	v_mov_b32_e32 v16, v3
	v_mov_b32_e32 v17, v3
	v_mov_b32_e32 v4, v3
	v_mov_b32_e32 v5, v3
	v_mov_b32_e32 v6, v3
	v_mov_b32_e32 v7, v3
	v_mov_b32_e32 v8, v3
	v_mov_b32_e32 v9, v3
	v_mov_b32_e32 v10, v3
	v_mov_b32_e32 v11, v3
	v_mov_b32_e32 v12, v3
	v_mov_b32_e32 v13, v3
	v_mov_b32_e32 v14, v3
	v_mov_b32_e32 v15, v3
	s_lshl_b32 s34, s12, 1
	s_lshl_b32 s35, s12, 9
	v_add_u32_e32 v190, 0xffffff80, v18
	v_mov_b32_e32 v2, v3
	v_mov_b64_e32 v[64:65], v[16:17]
	v_mov_b64_e32 v[80:81], v[16:17]
	v_mov_b64_e32 v[32:33], v[16:17]
	v_mov_b64_e32 v[48:49], v[16:17]
	s_mov_b32 s30, 63
	s_movk_i32 s31, 0xfe00
	v_add_u32_e32 v188, s34, v209
	s_add_i32 s36, s34, 2
	v_subrev_u32_e32 v189, s35, v228
	v_mov_b64_e32 v[62:63], v[14:15]
	v_mov_b64_e32 v[60:61], v[12:13]
	v_mov_b64_e32 v[58:59], v[10:11]
	v_mov_b64_e32 v[56:57], v[8:9]
	v_mov_b64_e32 v[54:55], v[6:7]
	v_mov_b64_e32 v[52:53], v[4:5]
	v_mov_b64_e32 v[50:51], v[2:3]
	v_mov_b64_e32 v[78:79], v[14:15]
	v_mov_b64_e32 v[76:77], v[12:13]
	v_mov_b64_e32 v[74:75], v[10:11]
	v_mov_b64_e32 v[72:73], v[8:9]
	v_mov_b64_e32 v[70:71], v[6:7]
	v_mov_b64_e32 v[68:69], v[4:5]
	v_mov_b64_e32 v[66:67], v[2:3]
	v_mov_b64_e32 v[30:31], v[14:15]
	v_mov_b64_e32 v[28:29], v[12:13]
	v_mov_b64_e32 v[26:27], v[10:11]
	v_mov_b64_e32 v[24:25], v[8:9]
	v_mov_b64_e32 v[22:23], v[6:7]
	v_mov_b64_e32 v[20:21], v[4:5]
	v_mov_b64_e32 v[18:19], v[2:3]
	v_mov_b64_e32 v[46:47], v[14:15]
	v_mov_b64_e32 v[44:45], v[12:13]
	v_mov_b64_e32 v[42:43], v[10:11]
	v_mov_b64_e32 v[40:41], v[8:9]
	v_mov_b64_e32 v[38:39], v[6:7]
	v_mov_b64_e32 v[36:37], v[4:5]
	v_mov_b64_e32 v[34:35], v[2:3]
	s_waitcnt vmcnt(11)
	ds_write_b128 v181, v[84:87]
	s_waitcnt vmcnt(10)
	ds_write_b128 v183, v[88:91]
	s_waitcnt vmcnt(9)
	ds_write_b128 v185, v[92:95] offset:32768
	s_waitcnt vmcnt(8)
	ds_write_b128 v230, v[96:99] offset:32768
	v_mul_f32_e32 v82, 0x3fb8aa3b, v82
	v_mov_b32_e32 v83, v82
	v_mov_b32_e32 v84, v82
	v_mov_b32_e32 v85, v82
	v_mov_b32_e32 v86, v82
	v_mov_b32_e32 v87, v82
	v_mov_b32_e32 v88, v82
	v_mov_b32_e32 v89, v82
	v_mov_b32_e32 v90, v82
	v_mov_b32_e32 v91, v82
	v_mov_b32_e32 v92, v82
	v_mov_b32_e32 v93, v82
	v_mov_b32_e32 v94, v82
	v_mov_b32_e32 v95, v82
	v_mov_b32_e32 v96, v82
	v_mov_b32_e32 v97, v82
	v_mov_b32_e32 v4, 0
	s_waitcnt lgkmcnt(0)
	s_barrier
	s_branch .LBB0_324

; __device__ __forceinline__ u32x4 pack8(const f32x4 a, const f32x4 b) { u32x4 w; w.x = cvt_pk_bf16(a[0], a[1]); w.y = cvt_pk_bf16(a[2], a[3]); w.z = cvt_pk_bf16(b[0], b[1]); w.w = cvt_pk_bf16(b[2], b[3]); return w; }
; __device__ __forceinline__ void unpack8(const u32x4 w, f32x4& a, f32x4& b) { a = (f32x4){bflo(w.x), bfhi(w.x), bflo(w.y), bfhi(w.y)}; b = (f32x4){bflo(w.z), bfhi(w.z), bflo(w.w), bfhi(w.w)}; }
;     __device__ __forceinline__ void operator()(const f32x4 (&acc)[2][2][4][2], const Unit& u, int wr, int wc, int fr, int fq) const {
;         const int row0 = u.pm * BM + wr * 64 + fr, col0 = u.pn * BM + wc * 32 + 8 * fq;
; #pragma unroll
;         for (int ai = 0; ai < 2; ++ai)
; #pragma unroll
;             for (int m = 0; m < 4; ++m) { const int row = row0 + ai * HALF + m * 16;
; #pragma unroll
;                 for (int bj = 0; bj < 2; ++bj) { const int c = col0 + bj * HALF;
;                     f32x4 g0, g1; unpack8(*(const u32x4*)(gates + (size_t)row * 4096 + STAGE * 2048 + c), g0, g1);
;                     f32x4 v0 = acc[ai][bj][m][0] * g0, v1 = acc[ai][bj][m][1] * g1;
;                     if (STAGE == 0) { *(u32x4*)(t1 + (size_t)row * 2048 + c) = pack8(v0, v1); }
.LBB0_925:
	s_andn2_b64 vcc, exec, s[2:3]
	s_mov_b64 s[2:3], -1
	v_lshl_add_u32 v249, s51, 8, v150
	v_lshl_or_b32 v248, s50, 8, v158
	v_lshlrev_b32_e32 v248, 1, v248
	v_lshl_add_u32 v246, v249, 13, v248
	v_lshl_add_u32 v247, v249, 12, v248
	v_mov_b32_e32 v248, v246
	global_load_dwordx4 v[144:147], v248, s[66:67] offset:0
	global_load_dwordx4 v[166:169], v248, s[66:67] offset:256
	v_add_u32_e32 v248, 0x20000, v246
	global_load_dwordx4 v[170:173], v248, s[66:67] offset:0
	global_load_dwordx4 v[174:177], v248, s[66:67] offset:256
	v_add_u32_e32 v248, 0x40000, v246
	global_load_dwordx4 v[178:181], v248, s[66:67] offset:0
	global_load_dwordx4 v[182:185], v248, s[66:67] offset:256
	v_add_u32_e32 v248, 0x60000, v246
	global_load_dwordx4 v[186:189], v248, s[66:67] offset:0
	global_load_dwordx4 v[190:193], v248, s[66:67] offset:256
	v_add_u32_e32 v248, 0x100000, v246
	global_load_dwordx4 v[200:203], v248, s[66:67] offset:0
	global_load_dwordx4 v[204:207], v248, s[66:67] offset:256
	v_add_u32_e32 v248, 0x120000, v246
	global_load_dwordx4 v[208:211], v248, s[66:67] offset:0
	global_load_dwordx4 v[212:215], v248, s[66:67] offset:256
	v_add_u32_e32 v248, 0x140000, v246
	global_load_dwordx4 v[216:219], v248, s[66:67] offset:0
	global_load_dwordx4 v[220:223], v248, s[66:67] offset:256
	v_add_u32_e32 v248, 0x160000, v246
	global_load_dwordx4 v[224:227], v248, s[66:67] offset:0
	global_load_dwordx4 v[228:231], v248, s[66:67] offset:256
	s_waitcnt vmcnt(15)
	v_lshlrev_b32_e32 v238, 16, v144
	v_and_b32_e32 v239, 0xffff0000, v144
	v_pk_mul_f32 v[126:127], v[126:127], v[238:239]
	v_lshlrev_b32_e32 v240, 16, v145
	v_and_b32_e32 v241, 0xffff0000, v145
	v_pk_mul_f32 v[128:129], v[128:129], v[240:241]
	v_lshlrev_b32_e32 v238, 16, v146
	v_and_b32_e32 v239, 0xffff0000, v146
	v_pk_mul_f32 v[122:123], v[122:123], v[238:239]
	v_lshlrev_b32_e32 v240, 16, v147
	v_and_b32_e32 v241, 0xffff0000, v147
	v_pk_mul_f32 v[124:125], v[124:125], v[240:241]
	v_cvt_pk_bf16_f32 v144, v126, v127
	v_cvt_pk_bf16_f32 v145, v128, v129
	v_cvt_pk_bf16_f32 v146, v122, v123
	v_cvt_pk_bf16_f32 v147, v124, v125
	v_mov_b32_e32 v248, v247
	global_store_dwordx4 v248, v[144:147], s[6:7] offset:0
	s_waitcnt vmcnt(15)
	v_lshlrev_b32_e32 v238, 16, v166
	v_and_b32_e32 v239, 0xffff0000, v166
	v_pk_mul_f32 v[114:115], v[114:115], v[238:239]
	v_lshlrev_b32_e32 v240, 16, v167
	v_and_b32_e32 v241, 0xffff0000, v167
	v_pk_mul_f32 v[116:117], v[116:117], v[240:241]
	v_lshlrev_b32_e32 v238, 16, v168
	v_and_b32_e32 v239, 0xffff0000, v168
	v_pk_mul_f32 v[110:111], v[110:111], v[238:239]
	v_lshlrev_b32_e32 v240, 16, v169
	v_and_b32_e32 v241, 0xffff0000, v169
	v_pk_mul_f32 v[112:113], v[112:113], v[240:241]
	v_cvt_pk_bf16_f32 v166, v114, v115
	v_cvt_pk_bf16_f32 v167, v116, v117
	v_cvt_pk_bf16_f32 v168, v110, v111
	v_cvt_pk_bf16_f32 v169, v112, v113
	global_store_dwordx4 v248, v[166:169], s[6:7] offset:256
	s_waitcnt vmcnt(15)
	v_lshlrev_b32_e32 v238, 16, v170
	v_and_b32_e32 v239, 0xffff0000, v170
	v_pk_mul_f32 v[118:119], v[118:119], v[238:239]
	v_lshlrev_b32_e32 v240, 16, v171
	v_and_b32_e32 v241, 0xffff0000, v171
	v_pk_mul_f32 v[120:121], v[120:121], v[240:241]
	v_lshlrev_b32_e32 v238, 16, v172
	v_and_b32_e32 v239, 0xffff0000, v172
	v_pk_mul_f32 v[106:107], v[106:107], v[238:239]
	v_lshlrev_b32_e32 v240, 16, v173
	v_and_b32_e32 v241, 0xffff0000, v173
	v_pk_mul_f32 v[108:109], v[108:109], v[240:241]
	v_cvt_pk_bf16_f32 v170, v118, v119
	v_cvt_pk_bf16_f32 v171, v120, v121
	v_cvt_pk_bf16_f32 v172, v106, v107
	v_cvt_pk_bf16_f32 v173, v108, v109
	v_add_u32_e32 v248, 0x10000, v247
	global_store_dwordx4 v248, v[170:173], s[6:7] offset:0
	s_waitcnt vmcnt(15)
	v_lshlrev_b32_e32 v238, 16, v174
	v_and_b32_e32 v239, 0xffff0000, v174
	v_pk_mul_f32 v[98:99], v[98:99], v[238:239]
	v_lshlrev_b32_e32 v240, 16, v175
	v_and_b32_e32 v241, 0xffff0000, v175
	v_pk_mul_f32 v[100:101], v[100:101], v[240:241]
	v_lshlrev_b32_e32 v238, 16, v176
	v_and_b32_e32 v239, 0xffff0000, v176
	v_pk_mul_f32 v[94:95], v[94:95], v[238:239]
	v_lshlrev_b32_e32 v240, 16, v177
	v_and_b32_e32 v241, 0xffff0000, v177
	v_pk_mul_f32 v[96:97], v[96:97], v[240:241]
	v_cvt_pk_bf16_f32 v174, v98, v99
	v_cvt_pk_bf16_f32 v175, v100, v101
	v_cvt_pk_bf16_f32 v176, v94, v95
	v_cvt_pk_bf16_f32 v177, v96, v97
	global_store_dwordx4 v248, v[174:177], s[6:7] offset:256
	s_waitcnt vmcnt(15)
	v_lshlrev_b32_e32 v238, 16, v178
	v_and_b32_e32 v239, 0xffff0000, v178
	v_pk_mul_f32 v[102:103], v[102:103], v[238:239]
	v_lshlrev_b32_e32 v240, 16, v179
	v_and_b32_e32 v241, 0xffff0000, v179
	v_pk_mul_f32 v[104:105], v[104:105], v[240:241]
	v_lshlrev_b32_e32 v238, 16, v180
	v_and_b32_e32 v239, 0xffff0000, v180
	v_pk_mul_f32 v[90:91], v[90:91], v[238:239]
	v_lshlrev_b32_e32 v240, 16, v181
	v_and_b32_e32 v241, 0xffff0000, v181
	v_pk_mul_f32 v[92:93], v[92:93], v[240:241]
	v_cvt_pk_bf16_f32 v178, v102, v103
	v_cvt_pk_bf16_f32 v179, v104, v105
	v_cvt_pk_bf16_f32 v180, v90, v91
	v_cvt_pk_bf16_f32 v181, v92, v93
	v_add_u32_e32 v248, 0x20000, v247
	global_store_dwordx4 v248, v[178:181], s[6:7] offset:0
	s_waitcnt vmcnt(15)
	v_lshlrev_b32_e32 v238, 16, v182
	v_and_b32_e32 v239, 0xffff0000, v182
	v_pk_mul_f32 v[82:83], v[82:83], v[238:239]
	v_lshlrev_b32_e32 v240, 16, v183
	v_and_b32_e32 v241, 0xffff0000, v183
	v_pk_mul_f32 v[84:85], v[84:85], v[240:241]
	v_lshlrev_b32_e32 v238, 16, v184
	v_and_b32_e32 v239, 0xffff0000, v184
	v_pk_mul_f32 v[78:79], v[78:79], v[238:239]
	v_lshlrev_b32_e32 v240, 16, v185
	v_and_b32_e32 v241, 0xffff0000, v185
	v_pk_mul_f32 v[80:81], v[80:81], v[240:241]
	v_cvt_pk_bf16_f32 v182, v82, v83
	v_cvt_pk_bf16_f32 v183, v84, v85
	v_cvt_pk_bf16_f32 v184, v78, v79
	v_cvt_pk_bf16_f32 v185, v80, v81
	global_store_dwordx4 v248, v[182:185], s[6:7] offset:256
	s_waitcnt vmcnt(15)
; __device__ __forceinline__ u32x4 pack8(const f32x4 a, const f32x4 b) { u32x4 w; w.x = cvt_pk_bf16(a[0], a[1]); w.y = cvt_pk_bf16(a[2], a[3]); w.z = cvt_pk_bf16(b[0], b[1]); w.w = cvt_pk_bf16(b[2], b[3]); return w; }
; __device__ __forceinline__ void unpack8(const u32x4 w, f32x4& a, f32x4& b) { a = (f32x4){bflo(w.x), bfhi(w.x), bflo(w.y), bfhi(w.y)}; b = (f32x4){bflo(w.z), bfhi(w.z), bflo(w.w), bfhi(w.w)}; }
;     __device__ __forceinline__ void operator()(const f32x4 (&acc)[2][2][4][2], const Unit& u, int wr, int wc, int fr, int fq) const {
;         const int row0 = u.pm * BM + wr * 64 + fr, col0 = u.pn * BM + wc * 32 + 8 * fq;
; #pragma unroll
;         for (int ai = 0; ai < 2; ++ai)
; #pragma unroll
;             for (int m = 0; m < 4; ++m) { const int row = row0 + ai * HALF + m * 16;
; #pragma unroll
;                 for (int bj = 0; bj < 2; ++bj) { const int c = col0 + bj * HALF;
;                     f32x4 g0, g1; unpack8(*(const u32x4*)(gates + (size_t)row * 4096 + STAGE * 2048 + c), g0, g1);
;                     f32x4 v0 = acc[ai][bj][m][0] * g0, v1 = acc[ai][bj][m][1] * g1;
;                     if (STAGE == 0) { *(u32x4*)(t1 + (size_t)row * 2048 + c) = pack8(v0, v1); }
	v_lshlrev_b32_e32 v238, 16, v186
	v_and_b32_e32 v239, 0xffff0000, v186
	v_pk_mul_f32 v[86:87], v[86:87], v[238:239]
	v_lshlrev_b32_e32 v240, 16, v187
	v_and_b32_e32 v241, 0xffff0000, v187
	v_pk_mul_f32 v[88:89], v[88:89], v[240:241]
	v_lshlrev_b32_e32 v238, 16, v188
	v_and_b32_e32 v239, 0xffff0000, v188
	v_pk_mul_f32 v[74:75], v[74:75], v[238:239]
	v_lshlrev_b32_e32 v240, 16, v189
	v_and_b32_e32 v241, 0xffff0000, v189
	v_pk_mul_f32 v[76:77], v[76:77], v[240:241]
	v_cvt_pk_bf16_f32 v186, v86, v87
	v_cvt_pk_bf16_f32 v187, v88, v89
	v_cvt_pk_bf16_f32 v188, v74, v75
	v_cvt_pk_bf16_f32 v189, v76, v77
	v_add_u32_e32 v248, 0x30000, v247
	global_store_dwordx4 v248, v[186:189], s[6:7] offset:0
	s_waitcnt vmcnt(15)
	v_lshlrev_b32_e32 v238, 16, v190
	v_and_b32_e32 v239, 0xffff0000, v190
	v_pk_mul_f32 v[70:71], v[70:71], v[238:239]
	v_lshlrev_b32_e32 v240, 16, v191
	v_and_b32_e32 v241, 0xffff0000, v191
	v_pk_mul_f32 v[72:73], v[72:73], v[240:241]
	v_lshlrev_b32_e32 v238, 16, v192
	v_and_b32_e32 v239, 0xffff0000, v192
	v_pk_mul_f32 v[66:67], v[66:67], v[238:239]
	v_lshlrev_b32_e32 v240, 16, v193
	v_and_b32_e32 v241, 0xffff0000, v193
	v_pk_mul_f32 v[68:69], v[68:69], v[240:241]
	v_cvt_pk_bf16_f32 v190, v70, v71
	v_cvt_pk_bf16_f32 v191, v72, v73
	v_cvt_pk_bf16_f32 v192, v66, v67
	v_cvt_pk_bf16_f32 v193, v68, v69
	global_store_dwordx4 v248, v[190:193], s[6:7] offset:256
	s_waitcnt vmcnt(15)
	v_lshlrev_b32_e32 v238, 16, v200
	v_and_b32_e32 v239, 0xffff0000, v200
	v_pk_mul_f32 v[62:63], v[62:63], v[238:239]
	v_lshlrev_b32_e32 v240, 16, v201
	v_and_b32_e32 v241, 0xffff0000, v201
	v_pk_mul_f32 v[64:65], v[64:65], v[240:241]
	v_lshlrev_b32_e32 v238, 16, v202
	v_and_b32_e32 v239, 0xffff0000, v202
	v_pk_mul_f32 v[58:59], v[58:59], v[238:239]
	v_lshlrev_b32_e32 v240, 16, v203
	v_and_b32_e32 v241, 0xffff0000, v203
	v_pk_mul_f32 v[60:61], v[60:61], v[240:241]
	v_cvt_pk_bf16_f32 v200, v62, v63
	v_cvt_pk_bf16_f32 v201, v64, v65
	v_cvt_pk_bf16_f32 v202, v58, v59
	v_cvt_pk_bf16_f32 v203, v60, v61
	v_add_u32_e32 v248, 0x80000, v247
	global_store_dwordx4 v248, v[200:203], s[6:7] offset:0
	s_waitcnt vmcnt(15)
	v_lshlrev_b32_e32 v238, 16, v204
	v_and_b32_e32 v239, 0xffff0000, v204
	v_pk_mul_f32 v[50:51], v[50:51], v[238:239]
	v_lshlrev_b32_e32 v240, 16, v205
	v_and_b32_e32 v241, 0xffff0000, v205
	v_pk_mul_f32 v[52:53], v[52:53], v[240:241]
	v_lshlrev_b32_e32 v238, 16, v206
	v_and_b32_e32 v239, 0xffff0000, v206
	v_pk_mul_f32 v[46:47], v[46:47], v[238:239]
	v_lshlrev_b32_e32 v240, 16, v207
	v_and_b32_e32 v241, 0xffff0000, v207
	v_pk_mul_f32 v[48:49], v[48:49], v[240:241]
	v_cvt_pk_bf16_f32 v204, v50, v51
	v_cvt_pk_bf16_f32 v205, v52, v53
	v_cvt_pk_bf16_f32 v206, v46, v47
	v_cvt_pk_bf16_f32 v207, v48, v49
	global_store_dwordx4 v248, v[204:207], s[6:7] offset:256
	s_waitcnt vmcnt(15)
	v_lshlrev_b32_e32 v238, 16, v208
	v_and_b32_e32 v239, 0xffff0000, v208
	v_pk_mul_f32 v[54:55], v[54:55], v[238:239]
	v_lshlrev_b32_e32 v240, 16, v209
	v_and_b32_e32 v241, 0xffff0000, v209
	v_pk_mul_f32 v[56:57], v[56:57], v[240:241]
	v_lshlrev_b32_e32 v238, 16, v210
	v_and_b32_e32 v239, 0xffff0000, v210
	v_pk_mul_f32 v[42:43], v[42:43], v[238:239]
	v_lshlrev_b32_e32 v240, 16, v211
	v_and_b32_e32 v241, 0xffff0000, v211
	v_pk_mul_f32 v[44:45], v[44:45], v[240:241]
	v_cvt_pk_bf16_f32 v208, v54, v55
	v_cvt_pk_bf16_f32 v209, v56, v57
	v_cvt_pk_bf16_f32 v210, v42, v43
	v_cvt_pk_bf16_f32 v211, v44, v45
	v_add_u32_e32 v248, 0x90000, v247
	global_store_dwordx4 v248, v[208:211], s[6:7] offset:0
	s_waitcnt vmcnt(15)
	v_lshlrev_b32_e32 v238, 16, v212
	v_and_b32_e32 v239, 0xffff0000, v212
	v_pk_mul_f32 v[34:35], v[34:35], v[238:239]
	v_lshlrev_b32_e32 v240, 16, v213
	v_and_b32_e32 v241, 0xffff0000, v213
	v_pk_mul_f32 v[36:37], v[36:37], v[240:241]
	v_lshlrev_b32_e32 v238, 16, v214
	v_and_b32_e32 v239, 0xffff0000, v214
	v_pk_mul_f32 v[30:31], v[30:31], v[238:239]
	v_lshlrev_b32_e32 v240, 16, v215
	v_and_b32_e32 v241, 0xffff0000, v215
	v_pk_mul_f32 v[32:33], v[32:33], v[240:241]
	v_cvt_pk_bf16_f32 v212, v34, v35
	v_cvt_pk_bf16_f32 v213, v36, v37
	v_cvt_pk_bf16_f32 v214, v30, v31
	v_cvt_pk_bf16_f32 v215, v32, v33
	global_store_dwordx4 v248, v[212:215], s[6:7] offset:256
	s_waitcnt vmcnt(15)
	v_lshlrev_b32_e32 v238, 16, v216
	v_and_b32_e32 v239, 0xffff0000, v216
	v_pk_mul_f32 v[38:39], v[38:39], v[238:239]
	v_lshlrev_b32_e32 v240, 16, v217
	v_and_b32_e32 v241, 0xffff0000, v217
	v_pk_mul_f32 v[40:41], v[40:41], v[240:241]
	v_lshlrev_b32_e32 v238, 16, v218
	v_and_b32_e32 v239, 0xffff0000, v218
	v_pk_mul_f32 v[26:27], v[26:27], v[238:239]
	v_lshlrev_b32_e32 v240, 16, v219
	v_and_b32_e32 v241, 0xffff0000, v219
	v_pk_mul_f32 v[28:29], v[28:29], v[240:241]
	v_cvt_pk_bf16_f32 v216, v38, v39
	v_cvt_pk_bf16_f32 v217, v40, v41
	v_cvt_pk_bf16_f32 v218, v26, v27
	v_cvt_pk_bf16_f32 v219, v28, v29
	v_add_u32_e32 v248, 0xa0000, v247
	global_store_dwordx4 v248, v[216:219], s[6:7] offset:0
	s_waitcnt vmcnt(15)
	v_lshlrev_b32_e32 v238, 16, v220
	v_and_b32_e32 v239, 0xffff0000, v220
	v_pk_mul_f32 v[18:19], v[18:19], v[238:239]
	v_lshlrev_b32_e32 v240, 16, v221
	v_and_b32_e32 v241, 0xffff0000, v221
	v_pk_mul_f32 v[20:21], v[20:21], v[240:241]
	v_lshlrev_b32_e32 v238, 16, v222
	v_and_b32_e32 v239, 0xffff0000, v222
	v_pk_mul_f32 v[14:15], v[14:15], v[238:239]
	v_lshlrev_b32_e32 v240, 16, v223
	v_and_b32_e32 v241, 0xffff0000, v223
	v_pk_mul_f32 v[16:17], v[16:17], v[240:241]
	v_cvt_pk_bf16_f32 v220, v18, v19
	v_cvt_pk_bf16_f32 v221, v20, v21
	v_cvt_pk_bf16_f32 v222, v14, v15
	v_cvt_pk_bf16_f32 v223, v16, v17
	global_store_dwordx4 v248, v[220:223], s[6:7] offset:256
	s_waitcnt vmcnt(15)
	v_lshlrev_b32_e32 v238, 16, v224
	v_and_b32_e32 v239, 0xffff0000, v224
	v_pk_mul_f32 v[22:23], v[22:23], v[238:239]
	v_lshlrev_b32_e32 v240, 16, v225
	v_and_b32_e32 v241, 0xffff0000, v225
	v_pk_mul_f32 v[24:25], v[24:25], v[240:241]
	v_lshlrev_b32_e32 v238, 16, v226
	v_and_b32_e32 v239, 0xffff0000, v226
	v_pk_mul_f32 v[10:11], v[10:11], v[238:239]
	v_lshlrev_b32_e32 v240, 16, v227
	v_and_b32_e32 v241, 0xffff0000, v227
	v_pk_mul_f32 v[12:13], v[12:13], v[240:241]
	v_cvt_pk_bf16_f32 v224, v22, v23
	v_cvt_pk_bf16_f32 v225, v24, v25
	v_cvt_pk_bf16_f32 v226, v10, v11
	v_cvt_pk_bf16_f32 v227, v12, v13
	v_add_u32_e32 v248, 0xb0000, v247
	global_store_dwordx4 v248, v[224:227], s[6:7] offset:0
	s_waitcnt vmcnt(15)
	v_lshlrev_b32_e32 v238, 16, v228
	v_and_b32_e32 v239, 0xffff0000, v228
	v_pk_mul_f32 v[6:7], v[6:7], v[238:239]
	v_lshlrev_b32_e32 v240, 16, v229
	v_and_b32_e32 v241, 0xffff0000, v229
	v_pk_mul_f32 v[8:9], v[8:9], v[240:241]
	v_lshlrev_b32_e32 v238, 16, v230
	v_and_b32_e32 v239, 0xffff0000, v230
	v_pk_mul_f32 v[2:3], v[2:3], v[238:239]
	v_lshlrev_b32_e32 v240, 16, v231
	v_and_b32_e32 v241, 0xffff0000, v231
	v_pk_mul_f32 v[4:5], v[4:5], v[240:241]
	v_cvt_pk_bf16_f32 v228, v6, v7
	v_cvt_pk_bf16_f32 v229, v8, v9
	v_cvt_pk_bf16_f32 v230, v2, v3
	v_cvt_pk_bf16_f32 v231, v4, v5
	global_store_dwordx4 v248, v[228:231], s[6:7] offset:256
	s_cmp_lg_u32 s45, 3
	s_cbranch_scc1 .Lp3b_skip0
; template <class Epi, class Sched, bool ALIGN_EPI = false, bool SP2 = false>
; __device__ __forceinline__ void gemm_phase(PG8_LAS unsigned char* lds, const Gemm g, const Sched& S, const Epi& E) {
;     ...
;         if constexpr (!Epi::AFTER_DRAIN) { E(acc, cur, wr, wc, fr, fq); S.done(cur); }
	s_waitcnt vmcnt(0)
	s_barrier
	v_readlane_b32 s32, v251, 21
	s_nop 3
	s_cmp_lg_u32 s32, 0
	s_cbranch_scc1 .Lp3b_skip0
	v_readlane_b32 s32, v250, 6
	s_nop 3
	s_lshl_b32 s32, s32, 6
	s_add_u32 s32, s32, 0x22500000
	v_mov_b32_e32 v248, s32
	v_mov_b32_e32 v249, 0
	v_readlane_b32 s32, v251, 26
	s_nop 1
	v_mov_b32_e32 v246, s32
	v_readlane_b32 s32, v251, 27
	s_nop 1
	v_mov_b32_e32 v247, s32
	v_lshl_add_u64 v[246:247], v[246:247], 0, v[248:249]
	buffer_wbl2 sc1
	s_waitcnt vmcnt(0)
	v_mov_b32_e32 v248, 0x13579bdf
	global_store_dword v[246:247], v248, off sc0 sc1
	s_waitcnt vmcnt(0)
.Lp3b_skip0:
	s_cbranch_vccnz .LBB0_920
	s_andn2_b64 vcc, exec, s[12:13]
	s_cbranch_vccnz .LBB0_919
	s_barrier
	s_branch .LBB0_919

; template <class Epi, class Sched, bool ALIGN_EPI = false, bool SP2 = false>
; __device__ __forceinline__ void gemm_phase(PG8_LAS unsigned char* lds, const Gemm g, const Sched& S, const Epi& E) {
;     ...
;         for (int a = 0; a < 2; ++a)
; #pragma unroll
;             for (int b = 0; b < 2; ++b)
; #pragma unroll
;                 for (int m = 0; m < 4; ++m)
; #pragma unroll
;                     for (int n = 0; n < 2; ++n) acc[a][b][m][n] = (f32x4){0.f, 0.f, 0.f, 0.f};
.LBB0_935:
	s_add_i32 s44, s44, 1
	s_mul_i32 s2, s44, s26
	s_mul_hi_u32 s3, s44, s82
	s_add_i32 s3, s3, s2
	s_mul_i32 s2, s44, s82
	s_mov_b64 s[28:29], s[18:19]
	s_add_u32 s18, s2, s68
	s_addc_u32 s19, s3, s27
	s_cmpk_lt_u32 s18, 0x200
	s_cbranch_scc1 .Lp3b_noadj
	s_cmpk_lt_u32 s68, 16
	s_cselect_b32 s2, 16, -16
	s_add_i32 s18, s18, s2
.Lp3b_noadj:
	v_cmp_lt_i64_e64 s[2:3], s[18:19], v[142:143]
	s_and_b64 s[30:31], s[2:3], exec
	s_cselect_b32 s9, s18, 0x20f
	s_ashr_i32 s11, s9, 31
	s_lshr_b32 s11, s11, 29
	s_add_i32 s11, s9, s11
	s_ashr_i32 s18, s11, 3
	s_and_b32 s11, s11, -8
	s_sub_i32 s9, s9, s11
	s_cmp_lt_i32 s9, 0
	s_movk_i32 s11, 0x43
	s_cselect_b32 s11, s11, 0x42
	s_mul_i32 s9, s9, s11
	s_add_i32 s9, s9, s18
	s_ashr_i32 s11, s9, 31
	s_lshr_b32 s11, s11, 26
	s_add_i32 s11, s9, s11
	s_ashr_i32 s18, s11, 6
	s_lshl_b32 s18, s18, 3
	s_sub_i32 s19, 0x42, s18
	s_min_i32 s19, s19, 8
	s_abs_i32 s34, s19
	v_cvt_f32_u32_e32 v2, s34
	s_andn2_b32 s11, s11, 63
	s_mov_b64 s[30:31], s[12:13]
	s_sub_i32 s9, s9, s11
	v_rcp_iflag_f32_e32 v2, v2
	s_sub_i32 s11, 0, s34
	s_mov_b32 s52, s10
	s_abs_i32 s10, s9
	v_mul_f32_e32 v2, 0x4f7ffffe, v2
	v_cvt_u32_f32_e32 v2, v2
	s_mov_b32 s51, s8
	s_xor_b32 s8, s9, s19
	s_ashr_i32 s8, s8, 31
	v_readfirstlane_b32 s12, v2
	s_mul_i32 s11, s11, s12
	s_mul_hi_u32 s11, s12, s11
	s_add_i32 s12, s12, s11
	s_mul_hi_u32 s11, s10, s12
	s_mul_i32 s12, s11, s34
	s_sub_i32 s10, s10, s12
	s_add_i32 s12, s11, 1
	s_sub_i32 s13, s10, s34
	s_cmp_ge_u32 s10, s34
	s_cselect_b32 s11, s12, s11
	s_cselect_b32 s10, s13, s10
	s_add_i32 s12, s11, 1
	s_cmp_ge_u32 s10, s34
	s_cselect_b32 s10, s12, s11
	s_xor_b32 s10, s10, s8
	s_sub_i32 s8, s10, s8
	s_mul_i32 s10, s8, s19
	s_sub_i32 s9, s9, s10
	s_add_i32 s10, s18, s9
	s_ashr_i32 s11, s10, 31
	s_lshl_b64 s[12:13], s[10:11], 20
	s_add_u32 s18, s36, s12
	s_addc_u32 s19, s37, s13
	s_and_b64 s[12:13], s[2:3], exec
	s_cselect_b32 s11, s19, s29
	s_cselect_b32 s53, s18, s28
	s_ashr_i32 s9, s8, 31
	s_lshl_b64 s[12:13], s[8:9], 20
	s_add_u32 s12, s38, s12
	s_addc_u32 s13, s39, s13
	s_and_b64 s[34:35], s[2:3], exec
	s_cselect_b32 s9, s13, s31
	s_cselect_b32 s54, s12, s30
	s_add_u32 s28, s28, 0x80080
	s_addc_u32 s29, s29, 0
	s_add_u32 s55, s30, 0x100
	s_addc_u32 s57, s31, 0
	s_mov_b32 s58, -2
	v_mov_b32_e32 v2, 0
	v_mov_b32_e32 v3, v139
	v_mov_b32_e32 v4, v139
	v_mov_b32_e32 v5, v139
	v_mov_b32_e32 v6, 0
	v_mov_b32_e32 v7, v139
	v_mov_b32_e32 v8, v139
	v_mov_b32_e32 v9, v139
	v_mov_b32_e32 v18, 0
	v_mov_b32_e32 v19, v139
	v_mov_b32_e32 v20, v139
	v_mov_b32_e32 v21, v139
	v_mov_b32_e32 v22, 0
	v_mov_b32_e32 v23, v139
	v_mov_b32_e32 v24, v139
	v_mov_b32_e32 v25, v139
	v_mov_b32_e32 v34, 0
	v_mov_b32_e32 v35, v139
	v_mov_b32_e32 v36, v139
	v_mov_b32_e32 v37, v139
	v_mov_b32_e32 v38, 0
	v_mov_b32_e32 v39, v139
	v_mov_b32_e32 v40, v139
	v_mov_b32_e32 v41, v139
	v_mov_b32_e32 v50, 0
	v_mov_b32_e32 v51, v139
	v_mov_b32_e32 v52, v139
	v_mov_b32_e32 v53, v139
	v_mov_b32_e32 v54, 0
	v_mov_b32_e32 v55, v139
	v_mov_b32_e32 v56, v139
	v_mov_b32_e32 v57, v139
	v_mov_b32_e32 v10, 0
	v_mov_b32_e32 v11, v139
	v_mov_b32_e32 v12, v139
	v_mov_b32_e32 v13, v139
	v_mov_b32_e32 v14, 0
	v_mov_b32_e32 v15, v139
	v_mov_b32_e32 v16, v139
	v_mov_b32_e32 v17, v139
	v_mov_b32_e32 v26, 0
	v_mov_b32_e32 v27, v139
	v_mov_b32_e32 v28, v139
	v_mov_b32_e32 v29, v139
	v_mov_b32_e32 v30, 0
	v_mov_b32_e32 v31, v139
	v_mov_b32_e32 v32, v139
	v_mov_b32_e32 v33, v139
	v_mov_b32_e32 v42, 0
	v_mov_b32_e32 v43, v139
	v_mov_b32_e32 v44, v139
	v_mov_b32_e32 v45, v139
	v_mov_b32_e32 v46, 0
	v_mov_b32_e32 v47, v139
	v_mov_b32_e32 v48, v139
	v_mov_b32_e32 v49, v139
	v_mov_b32_e32 v58, 0
	v_mov_b32_e32 v59, v139
	v_mov_b32_e32 v60, v139
	v_mov_b32_e32 v61, v139
	v_mov_b32_e32 v62, 0
	v_mov_b32_e32 v63, v139
	v_mov_b32_e32 v64, v139
	v_mov_b32_e32 v65, v139
	v_mov_b32_e32 v66, 0
	v_mov_b32_e32 v67, v139
	v_mov_b32_e32 v68, v139
	v_mov_b32_e32 v69, v139
	v_mov_b32_e32 v70, 0
	v_mov_b32_e32 v71, v139
	v_mov_b32_e32 v72, v139
	v_mov_b32_e32 v73, v139
	v_mov_b32_e32 v82, 0
	v_mov_b32_e32 v83, v139
	v_mov_b32_e32 v84, v139
	v_mov_b32_e32 v85, v139
	v_mov_b32_e32 v86, 0
	v_mov_b32_e32 v87, v139
	v_mov_b32_e32 v88, v139
	v_mov_b32_e32 v89, v139
	v_mov_b32_e32 v98, 0
	v_mov_b32_e32 v99, v139
	v_mov_b32_e32 v100, v139
	v_mov_b32_e32 v101, v139
	v_mov_b32_e32 v102, 0
	v_mov_b32_e32 v103, v139
	v_mov_b32_e32 v104, v139
	v_mov_b32_e32 v105, v139
	v_mov_b32_e32 v114, 0
	v_mov_b32_e32 v115, v139
	v_mov_b32_e32 v116, v139
	v_mov_b32_e32 v117, v139
	v_mov_b32_e32 v118, 0
	v_mov_b32_e32 v119, v139
	v_mov_b32_e32 v120, v139
	v_mov_b32_e32 v121, v139
	v_mov_b32_e32 v74, 0
	v_mov_b32_e32 v75, v139
	v_mov_b32_e32 v76, v139
	v_mov_b32_e32 v77, v139
	v_mov_b32_e32 v78, 0
	v_mov_b32_e32 v79, v139
	v_mov_b32_e32 v80, v139
	v_mov_b32_e32 v81, v139
	v_mov_b32_e32 v90, 0
	v_mov_b32_e32 v91, v139
	v_mov_b32_e32 v92, v139
	v_mov_b32_e32 v93, v139
	v_mov_b32_e32 v94, 0
	v_mov_b32_e32 v95, v139
	v_mov_b32_e32 v96, v139
	v_mov_b32_e32 v97, v139
	v_mov_b32_e32 v106, 0
	v_mov_b32_e32 v107, v139
	v_mov_b32_e32 v108, v139
	v_mov_b32_e32 v109, v139
	v_mov_b32_e32 v110, 0
	v_mov_b32_e32 v111, v139
	v_mov_b32_e32 v112, v139
	v_mov_b32_e32 v113, v139
	v_mov_b32_e32 v122, 0
	v_mov_b32_e32 v123, v139
	v_mov_b32_e32 v124, v139
	v_mov_b32_e32 v125, v139
	v_mov_b32_e32 v126, 0
	v_mov_b32_e32 v127, v139
	v_mov_b32_e32 v128, v139
	v_mov_b32_e32 v129, v139

; template <class Epi, class Sched, bool ALIGN_EPI = false, bool SP2 = false>
; __device__ __forceinline__ void gemm_phase(PG8_LAS unsigned char* lds, const Gemm g, const Sched& S, const Epi& E) {
;     ...
;         if constexpr (!Epi::AFTER_DRAIN) { E(acc, cur, wr, wc, fr, fq); S.done(cur); }
.LBB0_939:
	s_andn2_b64 vcc, exec, s[2:3]
	s_mov_b64 s[2:3], -1
	s_cmp_lg_u32 s44, 3
	s_cbranch_scc1 .Lp3b_skip1
	v_readlane_b32 s32, v250, 6
	s_nop 3
	s_add_i32 s32, s32, -16
	s_lshl_b32 s32, s32, 6
	s_add_u32 s32, s32, 0x22500000
	v_mov_b32_e32 v248, s32
	v_mov_b32_e32 v249, 0
	v_readlane_b32 s32, v251, 26
	s_nop 1
	v_mov_b32_e32 v246, s32
	v_readlane_b32 s32, v251, 27
	s_nop 1
	v_mov_b32_e32 v247, s32
	v_lshl_add_u64 v[246:247], v[246:247], 0, v[248:249]
	v_mov_b32_e32 v249, 0x4e20
.Lp3b_poll:
	global_load_dword v248, v[246:247], off sc0 sc1
	s_waitcnt vmcnt(0)
	v_readfirstlane_b32 s32, v248
	s_nop 3
	s_cmp_eq_u32 s32, 0x13579bdf
	s_cbranch_scc1 .Lp3b_got
	v_add_u32_e32 v249, -1, v249
	s_sleep 4
	v_readfirstlane_b32 s32, v249
	s_nop 3
	s_cmp_lg_u32 s32, 0
	s_cbranch_scc1 .Lp3b_poll

; __device__ __forceinline__ u32x4 pack8(const f32x4 a, const f32x4 b) { u32x4 w; w.x = cvt_pk_bf16(a[0], a[1]); w.y = cvt_pk_bf16(a[2], a[3]); w.z = cvt_pk_bf16(b[0], b[1]); w.w = cvt_pk_bf16(b[2], b[3]); return w; }
; __device__ __forceinline__ void unpack8(const u32x4 w, f32x4& a, f32x4& b) { a = (f32x4){bflo(w.x), bfhi(w.x), bflo(w.y), bfhi(w.y)}; b = (f32x4){bflo(w.z), bfhi(w.z), bflo(w.w), bfhi(w.w)}; }
;     __device__ __forceinline__ void operator()(const f32x4 (&acc)[2][2][4][2], const Unit& u, int wr, int wc, int fr, int fq) const {
;     ...
;                     f32x4 g0, g1; unpack8(*(const u32x4*)(gates + (size_t)row * 4096 + STAGE * 2048 + c), g0, g1);
;                     f32x4 v0 = acc[ai][bj][m][0] * g0, v1 = acc[ai][bj][m][1] * g1;
;                     if (STAGE == 0) { *(u32x4*)(t1 + (size_t)row * 2048 + c) = pack8(v0, v1); }
;                     else { f32x4 t0, t1v; unpack8(*(const u32x4*)(t1 + (size_t)row * 2048 + c), t0, t1v); *(u32x4*)(g + (size_t)row * 2048 + c) = pack8(v0 + t0, v1 + t1v); } } }
.Lp3b_skip1:
	v_lshl_add_u32 v249, s52, 8, v150
	v_lshl_or_b32 v248, s51, 8, v152
	v_lshlrev_b32_e32 v248, 1, v248
	v_lshl_add_u32 v246, v249, 13, v248
	v_add_u32_e32 v246, 0x1000, v246
	v_lshl_add_u32 v247, v249, 12, v248
	v_mov_b32_e32 v248, v246
	global_load_dwordx4 v[144:147], v248, s[66:67] offset:0
	v_mov_b32_e32 v248, v247
	global_load_dwordx4 v[156:159], v248, s[6:7] offset:0
	v_mov_b32_e32 v248, v246
	global_load_dwordx4 v[160:163], v248, s[66:67] offset:256
	v_mov_b32_e32 v248, v247
	global_load_dwordx4 v[166:169], v248, s[6:7] offset:256
	v_add_u32_e32 v248, 0x20000, v246
	global_load_dwordx4 v[170:173], v248, s[66:67] offset:0
	v_add_u32_e32 v248, 0x10000, v247
	global_load_dwordx4 v[174:177], v248, s[6:7] offset:0
	v_add_u32_e32 v248, 0x20000, v246
	global_load_dwordx4 v[178:181], v248, s[66:67] offset:256
	v_add_u32_e32 v248, 0x10000, v247
	global_load_dwordx4 v[182:185], v248, s[6:7] offset:256
	v_add_u32_e32 v248, 0x40000, v246
	global_load_dwordx4 v[186:189], v248, s[66:67] offset:0
	v_add_u32_e32 v248, 0x20000, v247
	global_load_dwordx4 v[190:193], v248, s[6:7] offset:0
	v_add_u32_e32 v248, 0x40000, v246
	global_load_dwordx4 v[200:203], v248, s[66:67] offset:256
	v_add_u32_e32 v248, 0x20000, v247
	global_load_dwordx4 v[204:207], v248, s[6:7] offset:256
	v_add_u32_e32 v248, 0x60000, v246
	global_load_dwordx4 v[208:211], v248, s[66:67] offset:0
	v_add_u32_e32 v248, 0x30000, v247
	global_load_dwordx4 v[212:215], v248, s[6:7] offset:0
	v_add_u32_e32 v248, 0x60000, v246
	global_load_dwordx4 v[216:219], v248, s[66:67] offset:256
	v_add_u32_e32 v248, 0x30000, v247
	global_load_dwordx4 v[220:223], v248, s[6:7] offset:256
	s_waitcnt vmcnt(14)
	v_lshlrev_b32_e32 v238, 16, v144
	v_and_b32_e32 v239, 0xffff0000, v144
	v_lshlrev_b32_e32 v242, 16, v156
	v_and_b32_e32 v243, 0xffff0000, v156
	v_pk_fma_f32 v[126:127], v[126:127], v[238:239], v[242:243]
	v_lshlrev_b32_e32 v240, 16, v145
	v_and_b32_e32 v241, 0xffff0000, v145
	v_lshlrev_b32_e32 v244, 16, v157
	v_and_b32_e32 v245, 0xffff0000, v157
	v_pk_fma_f32 v[128:129], v[128:129], v[240:241], v[244:245]
	v_lshlrev_b32_e32 v238, 16, v146
	v_and_b32_e32 v239, 0xffff0000, v146
	v_lshlrev_b32_e32 v242, 16, v158
	v_and_b32_e32 v243, 0xffff0000, v158
	v_pk_fma_f32 v[122:123], v[122:123], v[238:239], v[242:243]
	v_lshlrev_b32_e32 v240, 16, v147
	v_and_b32_e32 v241, 0xffff0000, v147
	v_lshlrev_b32_e32 v244, 16, v159
	v_and_b32_e32 v245, 0xffff0000, v159
	v_pk_fma_f32 v[124:125], v[124:125], v[240:241], v[244:245]
	v_cvt_pk_bf16_f32 v144, v126, v127
	v_cvt_pk_bf16_f32 v145, v128, v129
	v_cvt_pk_bf16_f32 v146, v122, v123
	v_cvt_pk_bf16_f32 v147, v124, v125
	v_mov_b32_e32 v248, v247
	global_store_dwordx4 v248, v[144:147], s[0:1] offset:0
	v_add_u32_e32 v248, 0x80000, v247
	global_load_dwordx4 v[156:159], v248, s[6:7] offset:0
	v_add_u32_e32 v248, 0x100000, v246
	global_load_dwordx4 v[144:147], v248, s[66:67] offset:0
	s_waitcnt vmcnt(15)
	v_lshlrev_b32_e32 v238, 16, v160
	v_and_b32_e32 v239, 0xffff0000, v160
	v_lshlrev_b32_e32 v242, 16, v166
	v_and_b32_e32 v243, 0xffff0000, v166
	v_pk_fma_f32 v[118:119], v[118:119], v[238:239], v[242:243]
	v_lshlrev_b32_e32 v240, 16, v161
	v_and_b32_e32 v241, 0xffff0000, v161
	v_lshlrev_b32_e32 v244, 16, v167
	v_and_b32_e32 v245, 0xffff0000, v167
	v_pk_fma_f32 v[120:121], v[120:121], v[240:241], v[244:245]
	v_lshlrev_b32_e32 v238, 16, v162
	v_and_b32_e32 v239, 0xffff0000, v162
	v_lshlrev_b32_e32 v242, 16, v168
	v_and_b32_e32 v243, 0xffff0000, v168
	v_pk_fma_f32 v[114:115], v[114:115], v[238:239], v[242:243]
	v_lshlrev_b32_e32 v240, 16, v163
	v_and_b32_e32 v241, 0xffff0000, v163
	v_lshlrev_b32_e32 v244, 16, v169
	v_and_b32_e32 v245, 0xffff0000, v169
	v_pk_fma_f32 v[116:117], v[116:117], v[240:241], v[244:245]
	v_cvt_pk_bf16_f32 v160, v118, v119
	v_cvt_pk_bf16_f32 v161, v120, v121
	v_cvt_pk_bf16_f32 v162, v114, v115
	v_cvt_pk_bf16_f32 v163, v116, v117
	v_mov_b32_e32 v248, v247
	global_store_dwordx4 v248, v[160:163], s[0:1] offset:256
	v_add_u32_e32 v248, 0x80000, v247
	global_load_dwordx4 v[166:169], v248, s[6:7] offset:256
	v_add_u32_e32 v248, 0x100000, v246
	global_load_dwordx4 v[160:163], v248, s[66:67] offset:256
	s_waitcnt vmcnt(16)
	v_lshlrev_b32_e32 v238, 16, v170
	v_and_b32_e32 v239, 0xffff0000, v170
	v_lshlrev_b32_e32 v242, 16, v174
	v_and_b32_e32 v243, 0xffff0000, v174
	v_pk_fma_f32 v[110:111], v[110:111], v[238:239], v[242:243]
	v_lshlrev_b32_e32 v240, 16, v171
	v_and_b32_e32 v241, 0xffff0000, v171
	v_lshlrev_b32_e32 v244, 16, v175
	v_and_b32_e32 v245, 0xffff0000, v175
	v_pk_fma_f32 v[112:113], v[112:113], v[240:241], v[244:245]
	v_lshlrev_b32_e32 v238, 16, v172
	v_and_b32_e32 v239, 0xffff0000, v172
	v_lshlrev_b32_e32 v242, 16, v176
	v_and_b32_e32 v243, 0xffff0000, v176
	v_pk_fma_f32 v[106:107], v[106:107], v[238:239], v[242:243]
	v_lshlrev_b32_e32 v240, 16, v173
	v_and_b32_e32 v241, 0xffff0000, v173
	v_lshlrev_b32_e32 v244, 16, v177
	v_and_b32_e32 v245, 0xffff0000, v177
	v_pk_fma_f32 v[108:109], v[108:109], v[240:241], v[244:245]
	v_cvt_pk_bf16_f32 v170, v110, v111
	v_cvt_pk_bf16_f32 v171, v112, v113
	v_cvt_pk_bf16_f32 v172, v106, v107
	v_cvt_pk_bf16_f32 v173, v108, v109
	v_add_u32_e32 v248, 0x10000, v247
	global_store_dwordx4 v248, v[170:173], s[0:1] offset:0
	v_add_u32_e32 v248, 0x90000, v247
	global_load_dwordx4 v[174:177], v248, s[6:7] offset:0
	v_add_u32_e32 v248, 0x120000, v246
	global_load_dwordx4 v[170:173], v248, s[66:67] offset:0
	s_waitcnt vmcnt(17)
; __device__ __forceinline__ u32x4 pack8(const f32x4 a, const f32x4 b) { u32x4 w; w.x = cvt_pk_bf16(a[0], a[1]); w.y = cvt_pk_bf16(a[2], a[3]); w.z = cvt_pk_bf16(b[0], b[1]); w.w = cvt_pk_bf16(b[2], b[3]); return w; }
; __device__ __forceinline__ void unpack8(const u32x4 w, f32x4& a, f32x4& b) { a = (f32x4){bflo(w.x), bfhi(w.x), bflo(w.y), bfhi(w.y)}; b = (f32x4){bflo(w.z), bfhi(w.z), bflo(w.w), bfhi(w.w)}; }
;     __device__ __forceinline__ void operator()(const f32x4 (&acc)[2][2][4][2], const Unit& u, int wr, int wc, int fr, int fq) const {
;     ...
;                     f32x4 g0, g1; unpack8(*(const u32x4*)(gates + (size_t)row * 4096 + STAGE * 2048 + c), g0, g1);
;                     f32x4 v0 = acc[ai][bj][m][0] * g0, v1 = acc[ai][bj][m][1] * g1;
;                     if (STAGE == 0) { *(u32x4*)(t1 + (size_t)row * 2048 + c) = pack8(v0, v1); }
;                     else { f32x4 t0, t1v; unpack8(*(const u32x4*)(t1 + (size_t)row * 2048 + c), t0, t1v); *(u32x4*)(g + (size_t)row * 2048 + c) = pack8(v0 + t0, v1 + t1v); } } }
	v_lshlrev_b32_e32 v238, 16, v178
	v_and_b32_e32 v239, 0xffff0000, v178
	v_lshlrev_b32_e32 v242, 16, v182
	v_and_b32_e32 v243, 0xffff0000, v182
	v_pk_fma_f32 v[102:103], v[102:103], v[238:239], v[242:243]
	v_lshlrev_b32_e32 v240, 16, v179
	v_and_b32_e32 v241, 0xffff0000, v179
	v_lshlrev_b32_e32 v244, 16, v183
	v_and_b32_e32 v245, 0xffff0000, v183
	v_pk_fma_f32 v[104:105], v[104:105], v[240:241], v[244:245]
	v_lshlrev_b32_e32 v238, 16, v180
	v_and_b32_e32 v239, 0xffff0000, v180
	v_lshlrev_b32_e32 v242, 16, v184
	v_and_b32_e32 v243, 0xffff0000, v184
	v_pk_fma_f32 v[98:99], v[98:99], v[238:239], v[242:243]
	v_lshlrev_b32_e32 v240, 16, v181
	v_and_b32_e32 v241, 0xffff0000, v181
	v_lshlrev_b32_e32 v244, 16, v185
	v_and_b32_e32 v245, 0xffff0000, v185
	v_pk_fma_f32 v[100:101], v[100:101], v[240:241], v[244:245]
	v_cvt_pk_bf16_f32 v178, v102, v103
	v_cvt_pk_bf16_f32 v179, v104, v105
	v_cvt_pk_bf16_f32 v180, v98, v99
	v_cvt_pk_bf16_f32 v181, v100, v101
	v_add_u32_e32 v248, 0x10000, v247
	global_store_dwordx4 v248, v[178:181], s[0:1] offset:256
	v_add_u32_e32 v248, 0x90000, v247
	global_load_dwordx4 v[182:185], v248, s[6:7] offset:256
	v_add_u32_e32 v248, 0x120000, v246
	global_load_dwordx4 v[178:181], v248, s[66:67] offset:256
	s_waitcnt vmcnt(18)
	v_lshlrev_b32_e32 v238, 16, v186
	v_and_b32_e32 v239, 0xffff0000, v186
	v_lshlrev_b32_e32 v242, 16, v190
	v_and_b32_e32 v243, 0xffff0000, v190
	v_pk_fma_f32 v[94:95], v[94:95], v[238:239], v[242:243]
	v_lshlrev_b32_e32 v240, 16, v187
	v_and_b32_e32 v241, 0xffff0000, v187
	v_lshlrev_b32_e32 v244, 16, v191
	v_and_b32_e32 v245, 0xffff0000, v191
	v_pk_fma_f32 v[96:97], v[96:97], v[240:241], v[244:245]
	v_lshlrev_b32_e32 v238, 16, v188
	v_and_b32_e32 v239, 0xffff0000, v188
	v_lshlrev_b32_e32 v242, 16, v192
	v_and_b32_e32 v243, 0xffff0000, v192
	v_pk_fma_f32 v[90:91], v[90:91], v[238:239], v[242:243]
	v_lshlrev_b32_e32 v240, 16, v189
	v_and_b32_e32 v241, 0xffff0000, v189
	v_lshlrev_b32_e32 v244, 16, v193
	v_and_b32_e32 v245, 0xffff0000, v193
	v_pk_fma_f32 v[92:93], v[92:93], v[240:241], v[244:245]
	v_cvt_pk_bf16_f32 v186, v94, v95
	v_cvt_pk_bf16_f32 v187, v96, v97
	v_cvt_pk_bf16_f32 v188, v90, v91
	v_cvt_pk_bf16_f32 v189, v92, v93
	v_add_u32_e32 v248, 0x20000, v247
	global_store_dwordx4 v248, v[186:189], s[0:1] offset:0
	v_add_u32_e32 v248, 0xa0000, v247
	global_load_dwordx4 v[190:193], v248, s[6:7] offset:0
	v_add_u32_e32 v248, 0x140000, v246
	global_load_dwordx4 v[186:189], v248, s[66:67] offset:0
	s_waitcnt vmcnt(19)
	v_lshlrev_b32_e32 v238, 16, v200
	v_and_b32_e32 v239, 0xffff0000, v200
	v_lshlrev_b32_e32 v242, 16, v204
	v_and_b32_e32 v243, 0xffff0000, v204
	v_pk_fma_f32 v[86:87], v[86:87], v[238:239], v[242:243]
	v_lshlrev_b32_e32 v240, 16, v201
	v_and_b32_e32 v241, 0xffff0000, v201
	v_lshlrev_b32_e32 v244, 16, v205
	v_and_b32_e32 v245, 0xffff0000, v205
	v_pk_fma_f32 v[88:89], v[88:89], v[240:241], v[244:245]
	v_lshlrev_b32_e32 v238, 16, v202
	v_and_b32_e32 v239, 0xffff0000, v202
	v_lshlrev_b32_e32 v242, 16, v206
	v_and_b32_e32 v243, 0xffff0000, v206
	v_pk_fma_f32 v[82:83], v[82:83], v[238:239], v[242:243]
	v_lshlrev_b32_e32 v240, 16, v203
	v_and_b32_e32 v241, 0xffff0000, v203
	v_lshlrev_b32_e32 v244, 16, v207
	v_and_b32_e32 v245, 0xffff0000, v207
	v_pk_fma_f32 v[84:85], v[84:85], v[240:241], v[244:245]
	v_cvt_pk_bf16_f32 v200, v86, v87
	v_cvt_pk_bf16_f32 v201, v88, v89
	v_cvt_pk_bf16_f32 v202, v82, v83
	v_cvt_pk_bf16_f32 v203, v84, v85
	v_add_u32_e32 v248, 0x20000, v247
	global_store_dwordx4 v248, v[200:203], s[0:1] offset:256
	v_add_u32_e32 v248, 0xa0000, v247
	global_load_dwordx4 v[204:207], v248, s[6:7] offset:256
	v_add_u32_e32 v248, 0x140000, v246
	global_load_dwordx4 v[200:203], v248, s[66:67] offset:256
	s_waitcnt vmcnt(20)
	v_lshlrev_b32_e32 v238, 16, v208
	v_and_b32_e32 v239, 0xffff0000, v208
	v_lshlrev_b32_e32 v242, 16, v212
	v_and_b32_e32 v243, 0xffff0000, v212
	v_pk_fma_f32 v[78:79], v[78:79], v[238:239], v[242:243]
	v_lshlrev_b32_e32 v240, 16, v209
	v_and_b32_e32 v241, 0xffff0000, v209
	v_lshlrev_b32_e32 v244, 16, v213
	v_and_b32_e32 v245, 0xffff0000, v213
	v_pk_fma_f32 v[80:81], v[80:81], v[240:241], v[244:245]
	v_lshlrev_b32_e32 v238, 16, v210
	v_and_b32_e32 v239, 0xffff0000, v210
	v_lshlrev_b32_e32 v242, 16, v214
	v_and_b32_e32 v243, 0xffff0000, v214
	v_pk_fma_f32 v[74:75], v[74:75], v[238:239], v[242:243]
	v_lshlrev_b32_e32 v240, 16, v211
	v_and_b32_e32 v241, 0xffff0000, v211
	v_lshlrev_b32_e32 v244, 16, v215
	v_and_b32_e32 v245, 0xffff0000, v215
	v_pk_fma_f32 v[76:77], v[76:77], v[240:241], v[244:245]
	v_cvt_pk_bf16_f32 v208, v78, v79
	v_cvt_pk_bf16_f32 v209, v80, v81
	v_cvt_pk_bf16_f32 v210, v74, v75
	v_cvt_pk_bf16_f32 v211, v76, v77
	v_add_u32_e32 v248, 0x30000, v247
	global_store_dwordx4 v248, v[208:211], s[0:1] offset:0
	v_add_u32_e32 v248, 0xb0000, v247
	global_load_dwordx4 v[212:215], v248, s[6:7] offset:0
	v_add_u32_e32 v248, 0x160000, v246
	global_load_dwordx4 v[208:211], v248, s[66:67] offset:0
	s_waitcnt vmcnt(21)
	v_lshlrev_b32_e32 v238, 16, v216
	v_and_b32_e32 v239, 0xffff0000, v216
	v_lshlrev_b32_e32 v242, 16, v220
	v_and_b32_e32 v243, 0xffff0000, v220
	v_pk_fma_f32 v[70:71], v[70:71], v[238:239], v[242:243]
	v_lshlrev_b32_e32 v240, 16, v217
	v_and_b32_e32 v241, 0xffff0000, v217
	v_lshlrev_b32_e32 v244, 16, v221
	v_and_b32_e32 v245, 0xffff0000, v221
	v_pk_fma_f32 v[72:73], v[72:73], v[240:241], v[244:245]
	v_lshlrev_b32_e32 v238, 16, v218
	v_and_b32_e32 v239, 0xffff0000, v218
	v_lshlrev_b32_e32 v242, 16, v222
	v_and_b32_e32 v243, 0xffff0000, v222
	v_pk_fma_f32 v[66:67], v[66:67], v[238:239], v[242:243]
	v_lshlrev_b32_e32 v240, 16, v219
	v_and_b32_e32 v241, 0xffff0000, v219
	v_lshlrev_b32_e32 v244, 16, v223
	v_and_b32_e32 v245, 0xffff0000, v223
	v_pk_fma_f32 v[68:69], v[68:69], v[240:241], v[244:245]
	v_cvt_pk_bf16_f32 v216, v70, v71
	v_cvt_pk_bf16_f32 v217, v72, v73
	v_cvt_pk_bf16_f32 v218, v66, v67
	v_cvt_pk_bf16_f32 v219, v68, v69
	v_add_u32_e32 v248, 0x30000, v247
	global_store_dwordx4 v248, v[216:219], s[0:1] offset:256
	v_add_u32_e32 v248, 0xb0000, v247
	global_load_dwordx4 v[220:223], v248, s[6:7] offset:256
	v_add_u32_e32 v248, 0x160000, v246
	global_load_dwordx4 v[216:219], v248, s[66:67] offset:256
	s_waitcnt vmcnt(21)
; __device__ __forceinline__ u32x4 pack8(const f32x4 a, const f32x4 b) { u32x4 w; w.x = cvt_pk_bf16(a[0], a[1]); w.y = cvt_pk_bf16(a[2], a[3]); w.z = cvt_pk_bf16(b[0], b[1]); w.w = cvt_pk_bf16(b[2], b[3]); return w; }
; __device__ __forceinline__ void unpack8(const u32x4 w, f32x4& a, f32x4& b) { a = (f32x4){bflo(w.x), bfhi(w.x), bflo(w.y), bfhi(w.y)}; b = (f32x4){bflo(w.z), bfhi(w.z), bflo(w.w), bfhi(w.w)}; }
;     __device__ __forceinline__ void operator()(const f32x4 (&acc)[2][2][4][2], const Unit& u, int wr, int wc, int fr, int fq) const {
;     ...
;                     f32x4 g0, g1; unpack8(*(const u32x4*)(gates + (size_t)row * 4096 + STAGE * 2048 + c), g0, g1);
;                     f32x4 v0 = acc[ai][bj][m][0] * g0, v1 = acc[ai][bj][m][1] * g1;
;                     if (STAGE == 0) { *(u32x4*)(t1 + (size_t)row * 2048 + c) = pack8(v0, v1); }
;                     else { f32x4 t0, t1v; unpack8(*(const u32x4*)(t1 + (size_t)row * 2048 + c), t0, t1v); *(u32x4*)(g + (size_t)row * 2048 + c) = pack8(v0 + t0, v1 + t1v); } } }
	v_lshlrev_b32_e32 v238, 16, v144
	v_and_b32_e32 v239, 0xffff0000, v144
	v_lshlrev_b32_e32 v242, 16, v156
	v_and_b32_e32 v243, 0xffff0000, v156
	v_pk_fma_f32 v[62:63], v[62:63], v[238:239], v[242:243]
	v_lshlrev_b32_e32 v240, 16, v145
	v_and_b32_e32 v241, 0xffff0000, v145
	v_lshlrev_b32_e32 v244, 16, v157
	v_and_b32_e32 v245, 0xffff0000, v157
	v_pk_fma_f32 v[64:65], v[64:65], v[240:241], v[244:245]
	v_lshlrev_b32_e32 v238, 16, v146
	v_and_b32_e32 v239, 0xffff0000, v146
	v_lshlrev_b32_e32 v242, 16, v158
	v_and_b32_e32 v243, 0xffff0000, v158
	v_pk_fma_f32 v[58:59], v[58:59], v[238:239], v[242:243]
	v_lshlrev_b32_e32 v240, 16, v147
	v_and_b32_e32 v241, 0xffff0000, v147
	v_lshlrev_b32_e32 v244, 16, v159
	v_and_b32_e32 v245, 0xffff0000, v159
	v_pk_fma_f32 v[60:61], v[60:61], v[240:241], v[244:245]
	v_cvt_pk_bf16_f32 v144, v62, v63
	v_cvt_pk_bf16_f32 v145, v64, v65
	v_cvt_pk_bf16_f32 v146, v58, v59
	v_cvt_pk_bf16_f32 v147, v60, v61
	v_add_u32_e32 v248, 0x80000, v247
	global_store_dwordx4 v248, v[144:147], s[0:1] offset:0
	s_waitcnt vmcnt(19)
	v_lshlrev_b32_e32 v238, 16, v160
	v_and_b32_e32 v239, 0xffff0000, v160
	v_lshlrev_b32_e32 v242, 16, v166
	v_and_b32_e32 v243, 0xffff0000, v166
	v_pk_fma_f32 v[54:55], v[54:55], v[238:239], v[242:243]
	v_lshlrev_b32_e32 v240, 16, v161
	v_and_b32_e32 v241, 0xffff0000, v161
	v_lshlrev_b32_e32 v244, 16, v167
	v_and_b32_e32 v245, 0xffff0000, v167
	v_pk_fma_f32 v[56:57], v[56:57], v[240:241], v[244:245]
	v_lshlrev_b32_e32 v238, 16, v162
	v_and_b32_e32 v239, 0xffff0000, v162
	v_lshlrev_b32_e32 v242, 16, v168
	v_and_b32_e32 v243, 0xffff0000, v168
	v_pk_fma_f32 v[50:51], v[50:51], v[238:239], v[242:243]
	v_lshlrev_b32_e32 v240, 16, v163
	v_and_b32_e32 v241, 0xffff0000, v163
	v_lshlrev_b32_e32 v244, 16, v169
	v_and_b32_e32 v245, 0xffff0000, v169
	v_pk_fma_f32 v[52:53], v[52:53], v[240:241], v[244:245]
	v_cvt_pk_bf16_f32 v160, v54, v55
	v_cvt_pk_bf16_f32 v161, v56, v57
	v_cvt_pk_bf16_f32 v162, v50, v51
	v_cvt_pk_bf16_f32 v163, v52, v53
	v_add_u32_e32 v248, 0x80000, v247
	global_store_dwordx4 v248, v[160:163], s[0:1] offset:256
	s_waitcnt vmcnt(17)
	v_lshlrev_b32_e32 v238, 16, v170
	v_and_b32_e32 v239, 0xffff0000, v170
	v_lshlrev_b32_e32 v242, 16, v174
	v_and_b32_e32 v243, 0xffff0000, v174
	v_pk_fma_f32 v[46:47], v[46:47], v[238:239], v[242:243]
	v_lshlrev_b32_e32 v240, 16, v171
	v_and_b32_e32 v241, 0xffff0000, v171
	v_lshlrev_b32_e32 v244, 16, v175
	v_and_b32_e32 v245, 0xffff0000, v175
	v_pk_fma_f32 v[48:49], v[48:49], v[240:241], v[244:245]
	v_lshlrev_b32_e32 v238, 16, v172
	v_and_b32_e32 v239, 0xffff0000, v172
	v_lshlrev_b32_e32 v242, 16, v176
	v_and_b32_e32 v243, 0xffff0000, v176
	v_pk_fma_f32 v[42:43], v[42:43], v[238:239], v[242:243]
	v_lshlrev_b32_e32 v240, 16, v173
	v_and_b32_e32 v241, 0xffff0000, v173
	v_lshlrev_b32_e32 v244, 16, v177
	v_and_b32_e32 v245, 0xffff0000, v177
	v_pk_fma_f32 v[44:45], v[44:45], v[240:241], v[244:245]
	v_cvt_pk_bf16_f32 v170, v46, v47
	v_cvt_pk_bf16_f32 v171, v48, v49
	v_cvt_pk_bf16_f32 v172, v42, v43
	v_cvt_pk_bf16_f32 v173, v44, v45
	v_add_u32_e32 v248, 0x90000, v247
	global_store_dwordx4 v248, v[170:173], s[0:1] offset:0
	s_waitcnt vmcnt(15)
	v_lshlrev_b32_e32 v238, 16, v178
	v_and_b32_e32 v239, 0xffff0000, v178
	v_lshlrev_b32_e32 v242, 16, v182
	v_and_b32_e32 v243, 0xffff0000, v182
	v_pk_fma_f32 v[38:39], v[38:39], v[238:239], v[242:243]
	v_lshlrev_b32_e32 v240, 16, v179
	v_and_b32_e32 v241, 0xffff0000, v179
	v_lshlrev_b32_e32 v244, 16, v183
	v_and_b32_e32 v245, 0xffff0000, v183
	v_pk_fma_f32 v[40:41], v[40:41], v[240:241], v[244:245]
	v_lshlrev_b32_e32 v238, 16, v180
	v_and_b32_e32 v239, 0xffff0000, v180
	v_lshlrev_b32_e32 v242, 16, v184
	v_and_b32_e32 v243, 0xffff0000, v184
	v_pk_fma_f32 v[34:35], v[34:35], v[238:239], v[242:243]
	v_lshlrev_b32_e32 v240, 16, v181
	v_and_b32_e32 v241, 0xffff0000, v181
	v_lshlrev_b32_e32 v244, 16, v185
	v_and_b32_e32 v245, 0xffff0000, v185
	v_pk_fma_f32 v[36:37], v[36:37], v[240:241], v[244:245]
	v_cvt_pk_bf16_f32 v178, v38, v39
	v_cvt_pk_bf16_f32 v179, v40, v41
	v_cvt_pk_bf16_f32 v180, v34, v35
	v_cvt_pk_bf16_f32 v181, v36, v37
	v_add_u32_e32 v248, 0x90000, v247
	global_store_dwordx4 v248, v[178:181], s[0:1] offset:256
	s_waitcnt vmcnt(13)
; __device__ __forceinline__ u32x4 pack8(const f32x4 a, const f32x4 b) { u32x4 w; w.x = cvt_pk_bf16(a[0], a[1]); w.y = cvt_pk_bf16(a[2], a[3]); w.z = cvt_pk_bf16(b[0], b[1]); w.w = cvt_pk_bf16(b[2], b[3]); return w; }
; __device__ __forceinline__ void unpack8(const u32x4 w, f32x4& a, f32x4& b) { a = (f32x4){bflo(w.x), bfhi(w.x), bflo(w.y), bfhi(w.y)}; b = (f32x4){bflo(w.z), bfhi(w.z), bflo(w.w), bfhi(w.w)}; }
;     __device__ __forceinline__ void operator()(const f32x4 (&acc)[2][2][4][2], const Unit& u, int wr, int wc, int fr, int fq) const {
;     ...
;                     f32x4 g0, g1; unpack8(*(const u32x4*)(gates + (size_t)row * 4096 + STAGE * 2048 + c), g0, g1);
;                     f32x4 v0 = acc[ai][bj][m][0] * g0, v1 = acc[ai][bj][m][1] * g1;
;                     if (STAGE == 0) { *(u32x4*)(t1 + (size_t)row * 2048 + c) = pack8(v0, v1); }
;                     else { f32x4 t0, t1v; unpack8(*(const u32x4*)(t1 + (size_t)row * 2048 + c), t0, t1v); *(u32x4*)(g + (size_t)row * 2048 + c) = pack8(v0 + t0, v1 + t1v); } } }
	v_lshlrev_b32_e32 v238, 16, v186
	v_and_b32_e32 v239, 0xffff0000, v186
	v_lshlrev_b32_e32 v242, 16, v190
	v_and_b32_e32 v243, 0xffff0000, v190
	v_pk_fma_f32 v[30:31], v[30:31], v[238:239], v[242:243]
	v_lshlrev_b32_e32 v240, 16, v187
	v_and_b32_e32 v241, 0xffff0000, v187
	v_lshlrev_b32_e32 v244, 16, v191
	v_and_b32_e32 v245, 0xffff0000, v191
	v_pk_fma_f32 v[32:33], v[32:33], v[240:241], v[244:245]
	v_lshlrev_b32_e32 v238, 16, v188
	v_and_b32_e32 v239, 0xffff0000, v188
	v_lshlrev_b32_e32 v242, 16, v192
	v_and_b32_e32 v243, 0xffff0000, v192
	v_pk_fma_f32 v[26:27], v[26:27], v[238:239], v[242:243]
	v_lshlrev_b32_e32 v240, 16, v189
	v_and_b32_e32 v241, 0xffff0000, v189
	v_lshlrev_b32_e32 v244, 16, v193
	v_and_b32_e32 v245, 0xffff0000, v193
	v_pk_fma_f32 v[28:29], v[28:29], v[240:241], v[244:245]
	v_cvt_pk_bf16_f32 v186, v30, v31
	v_cvt_pk_bf16_f32 v187, v32, v33
	v_cvt_pk_bf16_f32 v188, v26, v27
	v_cvt_pk_bf16_f32 v189, v28, v29
	v_add_u32_e32 v248, 0xa0000, v247
	global_store_dwordx4 v248, v[186:189], s[0:1] offset:0
	s_waitcnt vmcnt(11)
	v_lshlrev_b32_e32 v238, 16, v200
	v_and_b32_e32 v239, 0xffff0000, v200
	v_lshlrev_b32_e32 v242, 16, v204
	v_and_b32_e32 v243, 0xffff0000, v204
	v_pk_fma_f32 v[22:23], v[22:23], v[238:239], v[242:243]
	v_lshlrev_b32_e32 v240, 16, v201
	v_and_b32_e32 v241, 0xffff0000, v201
	v_lshlrev_b32_e32 v244, 16, v205
	v_and_b32_e32 v245, 0xffff0000, v205
	v_pk_fma_f32 v[24:25], v[24:25], v[240:241], v[244:245]
	v_lshlrev_b32_e32 v238, 16, v202
	v_and_b32_e32 v239, 0xffff0000, v202
	v_lshlrev_b32_e32 v242, 16, v206
	v_and_b32_e32 v243, 0xffff0000, v206
	v_pk_fma_f32 v[18:19], v[18:19], v[238:239], v[242:243]
	v_lshlrev_b32_e32 v240, 16, v203
	v_and_b32_e32 v241, 0xffff0000, v203
	v_lshlrev_b32_e32 v244, 16, v207
	v_and_b32_e32 v245, 0xffff0000, v207
	v_pk_fma_f32 v[20:21], v[20:21], v[240:241], v[244:245]
	v_cvt_pk_bf16_f32 v200, v22, v23
	v_cvt_pk_bf16_f32 v201, v24, v25
	v_cvt_pk_bf16_f32 v202, v18, v19
	v_cvt_pk_bf16_f32 v203, v20, v21
	v_add_u32_e32 v248, 0xa0000, v247
	global_store_dwordx4 v248, v[200:203], s[0:1] offset:256
	s_waitcnt vmcnt(9)
	v_lshlrev_b32_e32 v238, 16, v208
	v_and_b32_e32 v239, 0xffff0000, v208
	v_lshlrev_b32_e32 v242, 16, v212
	v_and_b32_e32 v243, 0xffff0000, v212
	v_pk_fma_f32 v[14:15], v[14:15], v[238:239], v[242:243]
	v_lshlrev_b32_e32 v240, 16, v209
	v_and_b32_e32 v241, 0xffff0000, v209
	v_lshlrev_b32_e32 v244, 16, v213
	v_and_b32_e32 v245, 0xffff0000, v213
	v_pk_fma_f32 v[16:17], v[16:17], v[240:241], v[244:245]
	v_lshlrev_b32_e32 v238, 16, v210
	v_and_b32_e32 v239, 0xffff0000, v210
	v_lshlrev_b32_e32 v242, 16, v214
	v_and_b32_e32 v243, 0xffff0000, v214
	v_pk_fma_f32 v[10:11], v[10:11], v[238:239], v[242:243]
	v_lshlrev_b32_e32 v240, 16, v211
	v_and_b32_e32 v241, 0xffff0000, v211
	v_lshlrev_b32_e32 v244, 16, v215
	v_and_b32_e32 v245, 0xffff0000, v215
	v_pk_fma_f32 v[12:13], v[12:13], v[240:241], v[244:245]
	v_cvt_pk_bf16_f32 v208, v14, v15
	v_cvt_pk_bf16_f32 v209, v16, v17
	v_cvt_pk_bf16_f32 v210, v10, v11
	v_cvt_pk_bf16_f32 v211, v12, v13
	v_add_u32_e32 v248, 0xb0000, v247
	global_store_dwordx4 v248, v[208:211], s[0:1] offset:0
	s_waitcnt vmcnt(7)
	v_lshlrev_b32_e32 v238, 16, v216
	v_and_b32_e32 v239, 0xffff0000, v216
	v_lshlrev_b32_e32 v242, 16, v220
	v_and_b32_e32 v243, 0xffff0000, v220
	v_pk_fma_f32 v[6:7], v[6:7], v[238:239], v[242:243]
	v_lshlrev_b32_e32 v240, 16, v217
	v_and_b32_e32 v241, 0xffff0000, v217
	v_lshlrev_b32_e32 v244, 16, v221
	v_and_b32_e32 v245, 0xffff0000, v221
	v_pk_fma_f32 v[8:9], v[8:9], v[240:241], v[244:245]
	v_lshlrev_b32_e32 v238, 16, v218
	v_and_b32_e32 v239, 0xffff0000, v218
	v_lshlrev_b32_e32 v242, 16, v222
	v_and_b32_e32 v243, 0xffff0000, v222
	v_pk_fma_f32 v[2:3], v[2:3], v[238:239], v[242:243]
	v_lshlrev_b32_e32 v240, 16, v219
	v_and_b32_e32 v241, 0xffff0000, v219
	v_lshlrev_b32_e32 v244, 16, v223
	v_and_b32_e32 v245, 0xffff0000, v223
	v_pk_fma_f32 v[4:5], v[4:5], v[240:241], v[244:245]
	v_cvt_pk_bf16_f32 v216, v6, v7
	v_cvt_pk_bf16_f32 v217, v8, v9
	v_cvt_pk_bf16_f32 v218, v2, v3
	v_cvt_pk_bf16_f32 v219, v4, v5
	v_add_u32_e32 v248, 0xb0000, v247
	global_store_dwordx4 v248, v[216:219], s[0:1] offset:256
	s_cbranch_vccnz .LBB0_934
	s_andn2_b64 vcc, exec, s[14:15]
	s_cbranch_vccnz .LBB0_933
	s_barrier
	s_branch .LBB0_933
